# accumulator zeroing removed: first K-tile trip peeled with SrcC=0 on each accumulator's first MFMA
# speedup vs baseline: 1.0034x; 1.0034x over previous
.LBB0_354:
	s_ashr_i32 s13, s12, 31
	s_lshl_b64 s[14:15], s[12:13], 20
	s_add_u32 s14, s41, s14
	s_addc_u32 s15, s42, s15
	s_and_b64 s[16:17], s[4:5], exec
	s_cselect_b32 s13, s15, s23
	s_cselect_b32 s91, s14, s22
	s_ashr_i32 s11, s10, 31
	s_lshl_b64 s[16:17], s[10:11], 20
	s_add_u32 s16, s45, s16
	s_addc_u32 s17, s65, s17
	s_and_b64 s[54:55], s[4:5], exec
	s_cselect_b32 s11, s17, s53
	s_cselect_b32 s92, s16, s52
	s_add_u32 s22, s22, 0x80080
	s_addc_u32 s23, s23, 0
	s_add_u32 s93, s52, 0x100
	v_mov_b32_e32 v4, 0
	s_addc_u32 s94, s53, 0
	s_mov_b32 s95, -2
	s_add_u32 s52, s22, 0xfff80080
	s_addc_u32 s53, s23, -1
	s_add_i32 s58, 0, 0x10000
	s_cmp_eq_u32 s95, 28
	s_cselect_b32 s55, s13, s53
	s_cselect_b32 s54, s91, s52
	v_add_u32_e32 v138, s58, v141
	s_cselect_b32 s53, s11, s94
	s_cselect_b32 s52, s92, s93
	s_add_i32 s59, 0, 0x14000
	ds_read_b128 v[144:147], v138
	ds_read_b128 v[148:151], v138 offset:1024
	ds_read_b128 v[152:155], v138 offset:2048
	ds_read_b128 v[156:159], v138 offset:3072
	v_add_u32_e32 v138, s59, v141
	ds_read_b128 v[160:163], v138
	ds_read_b128 v[164:167], v138 offset:1024
	ds_read_b128 v[168:171], v138 offset:2048
	ds_read_b128 v[172:175], v138 offset:3072
	v_lshl_add_u64 v[138:139], s[22:23], 0, v[134:135]
	s_add_i32 m0, s76, 0xc000
	ds_read_b128 v[176:179], v143
	ds_read_b128 v[180:183], v143 offset:1024
	ds_read_b128 v[184:187], v143 offset:2048
	ds_read_b128 v[188:191], v143 offset:3072
	ds_read_b128 v[196:199], v143 offset:4096
	ds_read_b128 v[200:203], v143 offset:5120
	ds_read_b128 v[204:207], v143 offset:6144
	ds_read_b128 v[208:211], v143 offset:7168
	global_load_lds_dwordx4 v[138:139], off
	v_lshl_add_u64 v[138:139], s[22:23], 0, v[136:137]
	s_add_i32 m0, s76, 0xe000
	s_nop 0
	global_load_lds_dwordx4 v[138:139], off
	s_waitcnt vmcnt(8)
	s_waitcnt lgkmcnt(0)
	s_barrier
	v_mfma_f32_16x16x32_bf16 v[120:123], v[144:147], v[176:179], 0
	v_mfma_f32_16x16x32_bf16 v[120:123], v[148:151], v[180:183], v[120:123]
	v_mfma_f32_16x16x32_bf16 v[104:107], v[144:147], v[184:187], 0
	v_mfma_f32_16x16x32_bf16 v[104:107], v[148:151], v[188:191], v[104:107]
	v_mfma_f32_16x16x32_bf16 v[88:91], v[144:147], v[196:199], 0
	v_mfma_f32_16x16x32_bf16 v[88:91], v[148:151], v[200:203], v[88:91]
	v_mfma_f32_16x16x32_bf16 v[72:75], v[144:147], v[204:207], 0
	v_mfma_f32_16x16x32_bf16 v[72:75], v[148:151], v[208:211], v[72:75]
	v_mfma_f32_16x16x32_bf16 v[112:115], v[152:155], v[176:179], 0
	v_mfma_f32_16x16x32_bf16 v[112:115], v[156:159], v[180:183], v[112:115]
	v_mfma_f32_16x16x32_bf16 v[96:99], v[152:155], v[184:187], 0
	v_mfma_f32_16x16x32_bf16 v[96:99], v[156:159], v[188:191], v[96:99]
	v_mfma_f32_16x16x32_bf16 v[80:83], v[152:155], v[196:199], 0
	v_mfma_f32_16x16x32_bf16 v[80:83], v[156:159], v[200:203], v[80:83]
	v_mfma_f32_16x16x32_bf16 v[64:67], v[152:155], v[204:207], 0
	v_mfma_f32_16x16x32_bf16 v[64:67], v[156:159], v[208:211], v[64:67]
	v_mfma_f32_16x16x32_bf16 v[124:127], v[160:163], v[176:179], 0
	v_mfma_f32_16x16x32_bf16 v[124:127], v[164:167], v[180:183], v[124:127]
	v_mfma_f32_16x16x32_bf16 v[108:111], v[160:163], v[184:187], 0
	v_mfma_f32_16x16x32_bf16 v[108:111], v[164:167], v[188:191], v[108:111]
	v_mfma_f32_16x16x32_bf16 v[92:95], v[160:163], v[196:199], 0
	v_mfma_f32_16x16x32_bf16 v[92:95], v[164:167], v[200:203], v[92:95]
	v_mfma_f32_16x16x32_bf16 v[76:79], v[160:163], v[204:207], 0
	v_mfma_f32_16x16x32_bf16 v[76:79], v[164:167], v[208:211], v[76:79]
	v_mfma_f32_16x16x32_bf16 v[116:119], v[168:171], v[176:179], 0
	v_mfma_f32_16x16x32_bf16 v[116:119], v[172:175], v[180:183], v[116:119]
	v_mfma_f32_16x16x32_bf16 v[100:103], v[168:171], v[184:187], 0
	v_mfma_f32_16x16x32_bf16 v[100:103], v[172:175], v[188:191], v[100:103]
	v_mfma_f32_16x16x32_bf16 v[84:87], v[168:171], v[196:199], 0
	v_mfma_f32_16x16x32_bf16 v[84:87], v[172:175], v[200:203], v[84:87]
	v_mfma_f32_16x16x32_bf16 v[68:71], v[168:171], v[204:207], 0
	v_mfma_f32_16x16x32_bf16 v[68:71], v[172:175], v[208:211], v[68:71]
	s_barrier
	s_add_i32 s58, s58, s50
	v_lshl_add_u64 v[138:139], s[52:53], 0, v[216:217]
	s_mov_b32 m0, s58
	ds_read_b128 v[176:179], v143 offset:16384
	ds_read_b128 v[180:183], v143 offset:17408
	ds_read_b128 v[184:187], v143 offset:18432
	ds_read_b128 v[188:191], v143 offset:19456
	ds_read_b128 v[196:199], v143 offset:20480
	ds_read_b128 v[200:203], v143 offset:21504
	ds_read_b128 v[204:207], v143 offset:22528
	ds_read_b128 v[208:211], v143 offset:23552
	global_load_lds_dwordx4 v[138:139], off
	s_add_i32 m0, s58, 0x2000
	s_add_u32 s96, s52, 0x80000
	v_lshl_add_u64 v[192:193], s[52:53], 0, v[132:133]
	s_addc_u32 s97, s53, 0
	s_add_i32 s58, s59, s50
	global_load_lds_dwordx4 v[192:193], off
	v_lshl_add_u64 v[212:213], s[96:97], 0, v[216:217]
	s_mov_b32 m0, s58
	v_lshl_add_u64 v[214:215], s[54:55], 0, v[130:131]
	global_load_lds_dwordx4 v[212:213], off
	v_lshl_add_u64 v[212:213], s[96:97], 0, v[132:133]
	s_add_i32 m0, s58, 0x2000
	s_nop 0
	global_load_lds_dwordx4 v[212:213], off
	v_lshl_add_u64 v[212:213], s[54:55], 0, v[128:129]
	s_mov_b32 m0, s76
	s_nop 0
	global_load_lds_dwordx4 v[212:213], off
	s_mov_b32 m0, s74
	s_nop 0
	global_load_lds_dwordx4 v[214:215], off
	s_waitcnt vmcnt(8)
	s_waitcnt lgkmcnt(0)
	s_barrier
	v_mfma_f32_16x16x32_bf16 v[56:59], v[144:147], v[176:179], 0
	v_mfma_f32_16x16x32_bf16 v[56:59], v[148:151], v[180:183], v[56:59]
	v_mfma_f32_16x16x32_bf16 v[40:43], v[144:147], v[184:187], 0
	v_mfma_f32_16x16x32_bf16 v[40:43], v[148:151], v[188:191], v[40:43]
	v_mfma_f32_16x16x32_bf16 v[24:27], v[144:147], v[196:199], 0
	v_mfma_f32_16x16x32_bf16 v[24:27], v[148:151], v[200:203], v[24:27]
	v_mfma_f32_16x16x32_bf16 v[8:11], v[144:147], v[204:207], 0
	v_mfma_f32_16x16x32_bf16 v[8:11], v[148:151], v[208:211], v[8:11]
	v_mfma_f32_16x16x32_bf16 v[48:51], v[152:155], v[176:179], 0
	v_mfma_f32_16x16x32_bf16 v[48:51], v[156:159], v[180:183], v[48:51]
	v_mfma_f32_16x16x32_bf16 v[32:35], v[152:155], v[184:187], 0
	v_mfma_f32_16x16x32_bf16 v[32:35], v[156:159], v[188:191], v[32:35]
	v_mfma_f32_16x16x32_bf16 v[16:19], v[152:155], v[196:199], 0
	v_mfma_f32_16x16x32_bf16 v[16:19], v[156:159], v[200:203], v[16:19]
	v_mfma_f32_16x16x32_bf16 v[0:3], v[152:155], v[204:207], 0
	v_mfma_f32_16x16x32_bf16 v[0:3], v[156:159], v[208:211], v[0:3]
	v_mfma_f32_16x16x32_bf16 v[60:63], v[160:163], v[176:179], 0
	v_mfma_f32_16x16x32_bf16 v[60:63], v[164:167], v[180:183], v[60:63]
	v_mfma_f32_16x16x32_bf16 v[44:47], v[160:163], v[184:187], 0
	v_mfma_f32_16x16x32_bf16 v[44:47], v[164:167], v[188:191], v[44:47]
	v_mfma_f32_16x16x32_bf16 v[28:31], v[160:163], v[196:199], 0
	v_mfma_f32_16x16x32_bf16 v[28:31], v[164:167], v[200:203], v[28:31]
	v_mfma_f32_16x16x32_bf16 v[12:15], v[160:163], v[204:207], 0
	v_mfma_f32_16x16x32_bf16 v[12:15], v[164:167], v[208:211], v[12:15]
	v_mfma_f32_16x16x32_bf16 v[52:55], v[168:171], v[176:179], 0
	v_mfma_f32_16x16x32_bf16 v[52:55], v[172:175], v[180:183], v[52:55]
	v_mfma_f32_16x16x32_bf16 v[36:39], v[168:171], v[184:187], 0
	v_mfma_f32_16x16x32_bf16 v[36:39], v[172:175], v[188:191], v[36:39]
	v_mfma_f32_16x16x32_bf16 v[20:23], v[168:171], v[196:199], 0
	v_mfma_f32_16x16x32_bf16 v[20:23], v[172:175], v[200:203], v[20:23]
	v_mfma_f32_16x16x32_bf16 v[4:7], v[168:171], v[204:207], 0
	v_mfma_f32_16x16x32_bf16 v[4:7], v[172:175], v[208:211], v[4:7]
	s_barrier
	s_add_i32 s58, 0, 0x18000
	s_add_i32 s59, 0, 0x1c000
	v_add_u32_e32 v156, s58, v141
	v_add_u32_e32 v172, s59, v141
	ds_read_b128 v[144:147], v156
	ds_read_b128 v[148:151], v156 offset:1024
	ds_read_b128 v[152:155], v156 offset:2048
	ds_read_b128 v[156:159], v156 offset:3072
	ds_read_b128 v[160:163], v172
	ds_read_b128 v[164:167], v172 offset:1024
	ds_read_b128 v[168:171], v172 offset:2048
	ds_read_b128 v[172:175], v172 offset:3072
	s_add_u32 s54, s54, 0x80000
	s_addc_u32 s55, s55, 0
	s_mov_b32 m0, s85
	v_lshl_add_u64 v[218:219], s[54:55], 0, v[128:129]
	ds_read_b128 v[176:179], v143 offset:32768
	ds_read_b128 v[180:183], v143 offset:33792
	ds_read_b128 v[184:187], v143 offset:34816
	ds_read_b128 v[188:191], v143 offset:35840
	ds_read_b128 v[196:199], v143 offset:36864
	ds_read_b128 v[200:203], v143 offset:37888
	ds_read_b128 v[204:207], v143 offset:38912
	ds_read_b128 v[208:211], v143 offset:39936
	global_load_lds_dwordx4 v[218:219], off
	v_lshl_add_u64 v[218:219], s[54:55], 0, v[130:131]
	s_mov_b32 m0, s86
	s_nop 0
	global_load_lds_dwordx4 v[218:219], off
	s_waitcnt vmcnt(8)
	s_waitcnt lgkmcnt(0)
	s_barrier
	v_mfma_f32_16x16x32_bf16 v[120:123], v[144:147], v[176:179], v[120:123]
	v_mfma_f32_16x16x32_bf16 v[120:123], v[148:151], v[180:183], v[120:123]
	v_mfma_f32_16x16x32_bf16 v[104:107], v[144:147], v[184:187], v[104:107]
	v_mfma_f32_16x16x32_bf16 v[104:107], v[148:151], v[188:191], v[104:107]
	v_mfma_f32_16x16x32_bf16 v[88:91], v[144:147], v[196:199], v[88:91]
	v_mfma_f32_16x16x32_bf16 v[88:91], v[148:151], v[200:203], v[88:91]
	v_mfma_f32_16x16x32_bf16 v[72:75], v[144:147], v[204:207], v[72:75]
	v_mfma_f32_16x16x32_bf16 v[72:75], v[148:151], v[208:211], v[72:75]
	v_mfma_f32_16x16x32_bf16 v[112:115], v[152:155], v[176:179], v[112:115]
	v_mfma_f32_16x16x32_bf16 v[112:115], v[156:159], v[180:183], v[112:115]
	v_mfma_f32_16x16x32_bf16 v[96:99], v[152:155], v[184:187], v[96:99]
	v_mfma_f32_16x16x32_bf16 v[96:99], v[156:159], v[188:191], v[96:99]
	v_mfma_f32_16x16x32_bf16 v[80:83], v[152:155], v[196:199], v[80:83]
	v_mfma_f32_16x16x32_bf16 v[80:83], v[156:159], v[200:203], v[80:83]
	v_mfma_f32_16x16x32_bf16 v[64:67], v[152:155], v[204:207], v[64:67]
	v_mfma_f32_16x16x32_bf16 v[64:67], v[156:159], v[208:211], v[64:67]
	v_mfma_f32_16x16x32_bf16 v[124:127], v[160:163], v[176:179], v[124:127]
	v_mfma_f32_16x16x32_bf16 v[124:127], v[164:167], v[180:183], v[124:127]
	v_mfma_f32_16x16x32_bf16 v[108:111], v[160:163], v[184:187], v[108:111]
	v_mfma_f32_16x16x32_bf16 v[108:111], v[164:167], v[188:191], v[108:111]
	v_mfma_f32_16x16x32_bf16 v[92:95], v[160:163], v[196:199], v[92:95]
	v_mfma_f32_16x16x32_bf16 v[92:95], v[164:167], v[200:203], v[92:95]
	v_mfma_f32_16x16x32_bf16 v[76:79], v[160:163], v[204:207], v[76:79]
	v_mfma_f32_16x16x32_bf16 v[76:79], v[164:167], v[208:211], v[76:79]
	v_mfma_f32_16x16x32_bf16 v[116:119], v[168:171], v[176:179], v[116:119]
	v_mfma_f32_16x16x32_bf16 v[116:119], v[172:175], v[180:183], v[116:119]
	v_mfma_f32_16x16x32_bf16 v[100:103], v[168:171], v[184:187], v[100:103]
	v_mfma_f32_16x16x32_bf16 v[100:103], v[172:175], v[188:191], v[100:103]
	v_mfma_f32_16x16x32_bf16 v[84:87], v[168:171], v[196:199], v[84:87]
	v_mfma_f32_16x16x32_bf16 v[84:87], v[172:175], v[200:203], v[84:87]
	v_mfma_f32_16x16x32_bf16 v[68:71], v[168:171], v[204:207], v[68:71]
	v_mfma_f32_16x16x32_bf16 v[68:71], v[172:175], v[208:211], v[68:71]
	s_barrier
	s_add_i32 s54, s58, s50
	v_lshl_add_u64 v[138:139], v[138:139], 0, s[60:61]
	s_mov_b32 m0, s54
	ds_read_b128 v[176:179], v143 offset:49152
	ds_read_b128 v[180:183], v143 offset:50176
	ds_read_b128 v[184:187], v143 offset:51200
	ds_read_b128 v[188:191], v143 offset:52224
	ds_read_b128 v[196:199], v143 offset:53248
	ds_read_b128 v[200:203], v143 offset:54272
	ds_read_b128 v[204:207], v143 offset:55296
	ds_read_b128 v[208:211], v143 offset:56320
	global_load_lds_dwordx4 v[138:139], off
	s_add_i32 m0, s54, 0x2000
	s_add_u32 s52, s52, 0x80080
	v_lshl_add_u64 v[138:139], v[192:193], 0, s[60:61]
	s_addc_u32 s53, s53, 0
	s_add_i32 s54, s59, s50
	global_load_lds_dwordx4 v[138:139], off
	v_lshl_add_u64 v[138:139], s[52:53], 0, v[216:217]
	s_mov_b32 m0, s54
	s_nop 0
	global_load_lds_dwordx4 v[138:139], off
	v_lshl_add_u64 v[138:139], s[52:53], 0, v[132:133]
	s_add_i32 m0, s54, 0x2000
	s_nop 0
	global_load_lds_dwordx4 v[138:139], off
	v_lshl_add_u64 v[138:139], v[212:213], 0, s[60:61]
	s_mov_b32 m0, s87
	s_nop 0
	global_load_lds_dwordx4 v[138:139], off
	v_lshl_add_u64 v[138:139], v[214:215], 0, s[60:61]
	s_mov_b32 m0, s88
	s_nop 0
	global_load_lds_dwordx4 v[138:139], off
	s_waitcnt vmcnt(8)
	s_waitcnt lgkmcnt(0)
	s_barrier
	v_mfma_f32_16x16x32_bf16 v[56:59], v[144:147], v[176:179], v[56:59]
	v_mfma_f32_16x16x32_bf16 v[56:59], v[148:151], v[180:183], v[56:59]
	v_mfma_f32_16x16x32_bf16 v[40:43], v[144:147], v[184:187], v[40:43]
	v_mfma_f32_16x16x32_bf16 v[40:43], v[148:151], v[188:191], v[40:43]
	v_mfma_f32_16x16x32_bf16 v[24:27], v[144:147], v[196:199], v[24:27]
	v_mfma_f32_16x16x32_bf16 v[24:27], v[148:151], v[200:203], v[24:27]
	v_mfma_f32_16x16x32_bf16 v[8:11], v[144:147], v[204:207], v[8:11]
	v_mfma_f32_16x16x32_bf16 v[8:11], v[148:151], v[208:211], v[8:11]
	v_mfma_f32_16x16x32_bf16 v[48:51], v[152:155], v[176:179], v[48:51]
	v_mfma_f32_16x16x32_bf16 v[48:51], v[156:159], v[180:183], v[48:51]
	v_mfma_f32_16x16x32_bf16 v[32:35], v[152:155], v[184:187], v[32:35]
	v_mfma_f32_16x16x32_bf16 v[32:35], v[156:159], v[188:191], v[32:35]
	v_mfma_f32_16x16x32_bf16 v[16:19], v[152:155], v[196:199], v[16:19]
	v_mfma_f32_16x16x32_bf16 v[16:19], v[156:159], v[200:203], v[16:19]
	v_mfma_f32_16x16x32_bf16 v[0:3], v[152:155], v[204:207], v[0:3]
	v_mfma_f32_16x16x32_bf16 v[0:3], v[156:159], v[208:211], v[0:3]
	v_mfma_f32_16x16x32_bf16 v[60:63], v[160:163], v[176:179], v[60:63]
	v_mfma_f32_16x16x32_bf16 v[60:63], v[164:167], v[180:183], v[60:63]
	v_mfma_f32_16x16x32_bf16 v[44:47], v[160:163], v[184:187], v[44:47]
	v_mfma_f32_16x16x32_bf16 v[44:47], v[164:167], v[188:191], v[44:47]
	v_mfma_f32_16x16x32_bf16 v[28:31], v[160:163], v[196:199], v[28:31]
	v_mfma_f32_16x16x32_bf16 v[28:31], v[164:167], v[200:203], v[28:31]
	v_mfma_f32_16x16x32_bf16 v[12:15], v[160:163], v[204:207], v[12:15]
	v_mfma_f32_16x16x32_bf16 v[12:15], v[164:167], v[208:211], v[12:15]
	v_mfma_f32_16x16x32_bf16 v[52:55], v[168:171], v[176:179], v[52:55]
	v_mfma_f32_16x16x32_bf16 v[52:55], v[172:175], v[180:183], v[52:55]
	v_mfma_f32_16x16x32_bf16 v[36:39], v[168:171], v[184:187], v[36:39]
	v_mfma_f32_16x16x32_bf16 v[36:39], v[172:175], v[188:191], v[36:39]
	v_mfma_f32_16x16x32_bf16 v[20:23], v[168:171], v[196:199], v[20:23]
	v_mfma_f32_16x16x32_bf16 v[20:23], v[172:175], v[200:203], v[20:23]
	v_mfma_f32_16x16x32_bf16 v[4:7], v[168:171], v[204:207], v[4:7]
	v_mfma_f32_16x16x32_bf16 v[4:7], v[172:175], v[208:211], v[4:7]
	s_barrier
	s_add_i32 s95, s95, 2
	s_add_u32 s22, s22, 0x100
	s_addc_u32 s23, s23, 0
	s_add_u32 s93, s93, 0x100
	s_addc_u32 s94, s94, 0
	s_cmp_gt_u32 s95, 29
	s_cbranch_scc0 .LBB0_355
	s_branch .Lzexit_0

.Lzexit_0:
	s_and_b64 vcc, exec, s[38:39]
	s_cbranch_vccz .LBB0_358
	s_barrier

.LBB0_559:
	s_add_u32 s94, s22, 0x100
	v_mov_b32_e32 v0, 0
	s_addc_u32 s95, s23, 0
	s_mov_b32 s96, -2
	s_add_u32 s22, s18, 0x100
	s_addc_u32 s23, s19, 0
	s_add_i32 s58, 0, 0x10000
	s_cmpk_eq_i32 s96, 0x54
	s_cselect_b32 s55, s7, s23
	s_cselect_b32 s54, s6, s22
	s_cselect_b32 s53, s17, s95
	s_cselect_b32 s52, s16, s94
	s_add_i32 s59, 0, 0x14000
	v_add_u32_e32 v140, s58, v196
	v_add_u32_e32 v166, s59, v196
	ds_read_b128 v[128:131], v140
	ds_read_b128 v[132:135], v140 offset:1024
	ds_read_b128 v[136:139], v140 offset:2048
	ds_read_b128 v[140:143], v140 offset:3072
	ds_read_b128 v[144:147], v166
	ds_read_b128 v[148:151], v166 offset:1024
	ds_read_b128 v[152:155], v166 offset:2048
	ds_read_b128 v[166:169], v166 offset:3072
	v_lshl_add_u64 v[208:209], s[18:19], 0, v[162:163]
	s_add_i32 m0, s76, 0xc000
	ds_read_b128 v[170:173], v198
	ds_read_b128 v[174:177], v198 offset:1024
	ds_read_b128 v[178:181], v198 offset:2048
	ds_read_b128 v[182:185], v198 offset:3072
	ds_read_b128 v[186:189], v198 offset:4096
	ds_read_b128 v[190:193], v198 offset:5120
	ds_read_b128 v[200:203], v198 offset:6144
	ds_read_b128 v[204:207], v198 offset:7168
	global_load_lds_dwordx4 v[208:209], off
	v_lshl_add_u64 v[208:209], s[18:19], 0, v[164:165]
	s_add_i32 m0, s76, 0xe000
	s_nop 0
	global_load_lds_dwordx4 v[208:209], off
	s_waitcnt vmcnt(8)
	s_waitcnt lgkmcnt(0)
	s_barrier
	v_mfma_f32_16x16x32_bf16 v[124:127], v[128:131], v[170:173], 0
	v_mfma_f32_16x16x32_bf16 v[124:127], v[132:135], v[174:177], v[124:127]
	v_mfma_f32_16x16x32_bf16 v[108:111], v[128:131], v[178:181], 0
	v_mfma_f32_16x16x32_bf16 v[108:111], v[132:135], v[182:185], v[108:111]
	v_mfma_f32_16x16x32_bf16 v[92:95], v[128:131], v[186:189], 0
	v_mfma_f32_16x16x32_bf16 v[92:95], v[132:135], v[190:193], v[92:95]
	v_mfma_f32_16x16x32_bf16 v[76:79], v[128:131], v[200:203], 0
	v_mfma_f32_16x16x32_bf16 v[76:79], v[132:135], v[204:207], v[76:79]
	v_mfma_f32_16x16x32_bf16 v[120:123], v[136:139], v[170:173], 0
	v_mfma_f32_16x16x32_bf16 v[120:123], v[140:143], v[174:177], v[120:123]
	v_mfma_f32_16x16x32_bf16 v[104:107], v[136:139], v[178:181], 0
	v_mfma_f32_16x16x32_bf16 v[104:107], v[140:143], v[182:185], v[104:107]
	v_mfma_f32_16x16x32_bf16 v[88:91], v[136:139], v[186:189], 0
	v_mfma_f32_16x16x32_bf16 v[88:91], v[140:143], v[190:193], v[88:91]
	v_mfma_f32_16x16x32_bf16 v[72:75], v[136:139], v[200:203], 0
	v_mfma_f32_16x16x32_bf16 v[72:75], v[140:143], v[204:207], v[72:75]
	v_mfma_f32_16x16x32_bf16 v[116:119], v[144:147], v[170:173], 0
	v_mfma_f32_16x16x32_bf16 v[116:119], v[148:151], v[174:177], v[116:119]
	v_mfma_f32_16x16x32_bf16 v[100:103], v[144:147], v[178:181], 0
	v_mfma_f32_16x16x32_bf16 v[100:103], v[148:151], v[182:185], v[100:103]
	v_mfma_f32_16x16x32_bf16 v[84:87], v[144:147], v[186:189], 0
	v_mfma_f32_16x16x32_bf16 v[84:87], v[148:151], v[190:193], v[84:87]
	v_mfma_f32_16x16x32_bf16 v[68:71], v[144:147], v[200:203], 0
	v_mfma_f32_16x16x32_bf16 v[68:71], v[148:151], v[204:207], v[68:71]
	v_mfma_f32_16x16x32_bf16 v[112:115], v[152:155], v[170:173], 0
	v_mfma_f32_16x16x32_bf16 v[112:115], v[166:169], v[174:177], v[112:115]
	v_mfma_f32_16x16x32_bf16 v[96:99], v[152:155], v[178:181], 0
	v_mfma_f32_16x16x32_bf16 v[96:99], v[166:169], v[182:185], v[96:99]
	v_mfma_f32_16x16x32_bf16 v[80:83], v[152:155], v[186:189], 0
	v_mfma_f32_16x16x32_bf16 v[80:83], v[166:169], v[190:193], v[80:83]
	v_mfma_f32_16x16x32_bf16 v[64:67], v[152:155], v[200:203], 0
	v_mfma_f32_16x16x32_bf16 v[64:67], v[166:169], v[204:207], v[64:67]
	s_barrier
	s_add_i32 s18, s58, s50
	v_lshl_add_u64 v[208:209], s[52:53], 0, v[216:217]
	s_mov_b32 m0, s18
	ds_read_b128 v[170:173], v198 offset:16384
	ds_read_b128 v[174:177], v198 offset:17408
	ds_read_b128 v[178:181], v198 offset:18432
	ds_read_b128 v[182:185], v198 offset:19456
	ds_read_b128 v[186:189], v198 offset:20480
	ds_read_b128 v[190:193], v198 offset:21504
	ds_read_b128 v[200:203], v198 offset:22528
	ds_read_b128 v[204:207], v198 offset:23552
	global_load_lds_dwordx4 v[208:209], off
	s_add_i32 m0, s18, 0x2000
	s_add_u32 s18, s52, 0x164000
	v_lshl_add_u64 v[210:211], s[52:53], 0, v[160:161]
	s_addc_u32 s19, s53, 0
	s_add_i32 s58, s59, s50
	global_load_lds_dwordx4 v[210:211], off
	v_lshl_add_u64 v[212:213], s[18:19], 0, v[216:217]
	s_mov_b32 m0, s58
	v_lshl_add_u64 v[214:215], s[54:55], 0, v[158:159]
	global_load_lds_dwordx4 v[212:213], off
	v_lshl_add_u64 v[212:213], s[18:19], 0, v[160:161]
	s_add_i32 m0, s58, 0x2000
	s_nop 0
	global_load_lds_dwordx4 v[212:213], off
	v_lshl_add_u64 v[212:213], s[54:55], 0, v[156:157]
	s_mov_b32 m0, s76
	s_nop 0
	global_load_lds_dwordx4 v[212:213], off
	s_mov_b32 m0, s45
	s_nop 0
	global_load_lds_dwordx4 v[214:215], off
	s_waitcnt vmcnt(8)
	s_waitcnt lgkmcnt(0)
	s_barrier
	v_mfma_f32_16x16x32_bf16 v[60:63], v[128:131], v[170:173], 0
	v_mfma_f32_16x16x32_bf16 v[60:63], v[132:135], v[174:177], v[60:63]
	v_mfma_f32_16x16x32_bf16 v[44:47], v[128:131], v[178:181], 0
	v_mfma_f32_16x16x32_bf16 v[44:47], v[132:135], v[182:185], v[44:47]
	v_mfma_f32_16x16x32_bf16 v[28:31], v[128:131], v[186:189], 0
	v_mfma_f32_16x16x32_bf16 v[28:31], v[132:135], v[190:193], v[28:31]
	v_mfma_f32_16x16x32_bf16 v[12:15], v[128:131], v[200:203], 0
	v_mfma_f32_16x16x32_bf16 v[12:15], v[132:135], v[204:207], v[12:15]
	v_mfma_f32_16x16x32_bf16 v[56:59], v[136:139], v[170:173], 0
	v_mfma_f32_16x16x32_bf16 v[56:59], v[140:143], v[174:177], v[56:59]
	v_mfma_f32_16x16x32_bf16 v[40:43], v[136:139], v[178:181], 0
	v_mfma_f32_16x16x32_bf16 v[40:43], v[140:143], v[182:185], v[40:43]
	v_mfma_f32_16x16x32_bf16 v[24:27], v[136:139], v[186:189], 0
	v_mfma_f32_16x16x32_bf16 v[24:27], v[140:143], v[190:193], v[24:27]
	v_mfma_f32_16x16x32_bf16 v[8:11], v[136:139], v[200:203], 0
	v_mfma_f32_16x16x32_bf16 v[8:11], v[140:143], v[204:207], v[8:11]
	v_mfma_f32_16x16x32_bf16 v[52:55], v[144:147], v[170:173], 0
	v_mfma_f32_16x16x32_bf16 v[52:55], v[148:151], v[174:177], v[52:55]
	v_mfma_f32_16x16x32_bf16 v[36:39], v[144:147], v[178:181], 0
	v_mfma_f32_16x16x32_bf16 v[36:39], v[148:151], v[182:185], v[36:39]
	v_mfma_f32_16x16x32_bf16 v[20:23], v[144:147], v[186:189], 0
	v_mfma_f32_16x16x32_bf16 v[20:23], v[148:151], v[190:193], v[20:23]
	v_mfma_f32_16x16x32_bf16 v[4:7], v[144:147], v[200:203], 0
	v_mfma_f32_16x16x32_bf16 v[4:7], v[148:151], v[204:207], v[4:7]
	v_mfma_f32_16x16x32_bf16 v[48:51], v[152:155], v[170:173], 0
	v_mfma_f32_16x16x32_bf16 v[48:51], v[166:169], v[174:177], v[48:51]
	v_mfma_f32_16x16x32_bf16 v[32:35], v[152:155], v[178:181], 0
	v_mfma_f32_16x16x32_bf16 v[32:35], v[166:169], v[182:185], v[32:35]
	v_mfma_f32_16x16x32_bf16 v[16:19], v[152:155], v[186:189], 0
	v_mfma_f32_16x16x32_bf16 v[16:19], v[166:169], v[190:193], v[16:19]
	v_mfma_f32_16x16x32_bf16 v[0:3], v[152:155], v[200:203], 0
	v_mfma_f32_16x16x32_bf16 v[0:3], v[166:169], v[204:207], v[0:3]
	s_barrier
	s_add_i32 s58, 0, 0x18000
	s_add_i32 s59, 0, 0x1c000
	v_add_u32_e32 v140, s58, v196
	v_add_u32_e32 v166, s59, v196
	ds_read_b128 v[128:131], v140
	ds_read_b128 v[132:135], v140 offset:1024
	ds_read_b128 v[136:139], v140 offset:2048
	ds_read_b128 v[140:143], v140 offset:3072
	ds_read_b128 v[144:147], v166
	ds_read_b128 v[148:151], v166 offset:1024
	ds_read_b128 v[152:155], v166 offset:2048
	ds_read_b128 v[166:169], v166 offset:3072
	s_add_u32 s18, s54, 0x164000
	s_addc_u32 s19, s55, 0
	s_mov_b32 m0, s65
	v_lshl_add_u64 v[218:219], s[18:19], 0, v[156:157]
	ds_read_b128 v[170:173], v198 offset:32768
	ds_read_b128 v[174:177], v198 offset:33792
	ds_read_b128 v[178:181], v198 offset:34816
	ds_read_b128 v[182:185], v198 offset:35840
	ds_read_b128 v[186:189], v198 offset:36864
	ds_read_b128 v[190:193], v198 offset:37888
	ds_read_b128 v[200:203], v198 offset:38912
	ds_read_b128 v[204:207], v198 offset:39936
	global_load_lds_dwordx4 v[218:219], off
	v_lshl_add_u64 v[218:219], s[18:19], 0, v[158:159]
	s_mov_b32 m0, s72
	s_nop 0
	global_load_lds_dwordx4 v[218:219], off
	s_waitcnt vmcnt(8)
	s_waitcnt lgkmcnt(0)
	s_barrier
	v_mfma_f32_16x16x32_bf16 v[124:127], v[128:131], v[170:173], v[124:127]
	v_mfma_f32_16x16x32_bf16 v[124:127], v[132:135], v[174:177], v[124:127]
	v_mfma_f32_16x16x32_bf16 v[108:111], v[128:131], v[178:181], v[108:111]
	v_mfma_f32_16x16x32_bf16 v[108:111], v[132:135], v[182:185], v[108:111]
	v_mfma_f32_16x16x32_bf16 v[92:95], v[128:131], v[186:189], v[92:95]
	v_mfma_f32_16x16x32_bf16 v[92:95], v[132:135], v[190:193], v[92:95]
	v_mfma_f32_16x16x32_bf16 v[76:79], v[128:131], v[200:203], v[76:79]
	v_mfma_f32_16x16x32_bf16 v[76:79], v[132:135], v[204:207], v[76:79]
	v_mfma_f32_16x16x32_bf16 v[120:123], v[136:139], v[170:173], v[120:123]
	v_mfma_f32_16x16x32_bf16 v[120:123], v[140:143], v[174:177], v[120:123]
	v_mfma_f32_16x16x32_bf16 v[104:107], v[136:139], v[178:181], v[104:107]
	v_mfma_f32_16x16x32_bf16 v[104:107], v[140:143], v[182:185], v[104:107]
	v_mfma_f32_16x16x32_bf16 v[88:91], v[136:139], v[186:189], v[88:91]
	v_mfma_f32_16x16x32_bf16 v[88:91], v[140:143], v[190:193], v[88:91]
	v_mfma_f32_16x16x32_bf16 v[72:75], v[136:139], v[200:203], v[72:75]
	v_mfma_f32_16x16x32_bf16 v[72:75], v[140:143], v[204:207], v[72:75]
	v_mfma_f32_16x16x32_bf16 v[116:119], v[144:147], v[170:173], v[116:119]
	v_mfma_f32_16x16x32_bf16 v[116:119], v[148:151], v[174:177], v[116:119]
	v_mfma_f32_16x16x32_bf16 v[100:103], v[144:147], v[178:181], v[100:103]
	v_mfma_f32_16x16x32_bf16 v[100:103], v[148:151], v[182:185], v[100:103]
	v_mfma_f32_16x16x32_bf16 v[84:87], v[144:147], v[186:189], v[84:87]
	v_mfma_f32_16x16x32_bf16 v[84:87], v[148:151], v[190:193], v[84:87]
	v_mfma_f32_16x16x32_bf16 v[68:71], v[144:147], v[200:203], v[68:71]
	v_mfma_f32_16x16x32_bf16 v[68:71], v[148:151], v[204:207], v[68:71]
	v_mfma_f32_16x16x32_bf16 v[112:115], v[152:155], v[170:173], v[112:115]
	v_mfma_f32_16x16x32_bf16 v[112:115], v[166:169], v[174:177], v[112:115]
	v_mfma_f32_16x16x32_bf16 v[96:99], v[152:155], v[178:181], v[96:99]
	v_mfma_f32_16x16x32_bf16 v[96:99], v[166:169], v[182:185], v[96:99]
	v_mfma_f32_16x16x32_bf16 v[80:83], v[152:155], v[186:189], v[80:83]
	v_mfma_f32_16x16x32_bf16 v[80:83], v[166:169], v[190:193], v[80:83]
	v_mfma_f32_16x16x32_bf16 v[64:67], v[152:155], v[200:203], v[64:67]
	v_mfma_f32_16x16x32_bf16 v[64:67], v[166:169], v[204:207], v[64:67]
	s_barrier
	s_add_i32 s18, s58, s50
	v_lshl_add_u64 v[208:209], v[208:209], 0, s[60:61]
	s_mov_b32 m0, s18
	ds_read_b128 v[170:173], v198 offset:49152
	ds_read_b128 v[174:177], v198 offset:50176
	ds_read_b128 v[178:181], v198 offset:51200
	ds_read_b128 v[182:185], v198 offset:52224
	ds_read_b128 v[186:189], v198 offset:53248
	ds_read_b128 v[190:193], v198 offset:54272
	ds_read_b128 v[200:203], v198 offset:55296
	ds_read_b128 v[204:207], v198 offset:56320
	global_load_lds_dwordx4 v[208:209], off
	s_add_i32 m0, s18, 0x2000
	s_add_u32 s18, s52, 0x164080
	v_lshl_add_u64 v[208:209], v[210:211], 0, s[60:61]
	s_addc_u32 s19, s53, 0
	s_add_i32 s52, s59, s50
	global_load_lds_dwordx4 v[208:209], off
	v_lshl_add_u64 v[208:209], s[18:19], 0, v[216:217]
	s_mov_b32 m0, s52
	s_nop 0
	global_load_lds_dwordx4 v[208:209], off
	v_lshl_add_u64 v[208:209], s[18:19], 0, v[160:161]
	s_add_i32 m0, s52, 0x2000
	s_nop 0
	global_load_lds_dwordx4 v[208:209], off
	v_lshl_add_u64 v[208:209], v[212:213], 0, s[60:61]
	s_mov_b32 m0, s86
	s_nop 0
	global_load_lds_dwordx4 v[208:209], off
	v_lshl_add_u64 v[208:209], v[214:215], 0, s[60:61]
	s_mov_b32 m0, s87
	s_nop 0
	global_load_lds_dwordx4 v[208:209], off
	s_waitcnt vmcnt(8)
	s_waitcnt lgkmcnt(0)
	s_barrier
	v_mfma_f32_16x16x32_bf16 v[60:63], v[128:131], v[170:173], v[60:63]
	v_mfma_f32_16x16x32_bf16 v[60:63], v[132:135], v[174:177], v[60:63]
	v_mfma_f32_16x16x32_bf16 v[44:47], v[128:131], v[178:181], v[44:47]
	v_mfma_f32_16x16x32_bf16 v[44:47], v[132:135], v[182:185], v[44:47]
	v_mfma_f32_16x16x32_bf16 v[28:31], v[128:131], v[186:189], v[28:31]
	v_mfma_f32_16x16x32_bf16 v[28:31], v[132:135], v[190:193], v[28:31]
	v_mfma_f32_16x16x32_bf16 v[12:15], v[128:131], v[200:203], v[12:15]
	v_mfma_f32_16x16x32_bf16 v[12:15], v[132:135], v[204:207], v[12:15]
	v_mfma_f32_16x16x32_bf16 v[56:59], v[136:139], v[170:173], v[56:59]
	v_mfma_f32_16x16x32_bf16 v[56:59], v[140:143], v[174:177], v[56:59]
	v_mfma_f32_16x16x32_bf16 v[40:43], v[136:139], v[178:181], v[40:43]
	v_mfma_f32_16x16x32_bf16 v[40:43], v[140:143], v[182:185], v[40:43]
	v_mfma_f32_16x16x32_bf16 v[24:27], v[136:139], v[186:189], v[24:27]
	v_mfma_f32_16x16x32_bf16 v[24:27], v[140:143], v[190:193], v[24:27]
	v_mfma_f32_16x16x32_bf16 v[8:11], v[136:139], v[200:203], v[8:11]
	v_mfma_f32_16x16x32_bf16 v[8:11], v[140:143], v[204:207], v[8:11]
	v_mfma_f32_16x16x32_bf16 v[52:55], v[144:147], v[170:173], v[52:55]
	v_mfma_f32_16x16x32_bf16 v[52:55], v[148:151], v[174:177], v[52:55]
	v_mfma_f32_16x16x32_bf16 v[36:39], v[144:147], v[178:181], v[36:39]
	v_mfma_f32_16x16x32_bf16 v[36:39], v[148:151], v[182:185], v[36:39]
	v_mfma_f32_16x16x32_bf16 v[20:23], v[144:147], v[186:189], v[20:23]
	v_mfma_f32_16x16x32_bf16 v[20:23], v[148:151], v[190:193], v[20:23]
	v_mfma_f32_16x16x32_bf16 v[4:7], v[144:147], v[200:203], v[4:7]
	v_mfma_f32_16x16x32_bf16 v[4:7], v[148:151], v[204:207], v[4:7]
	v_mfma_f32_16x16x32_bf16 v[48:51], v[152:155], v[170:173], v[48:51]
	v_mfma_f32_16x16x32_bf16 v[48:51], v[166:169], v[174:177], v[48:51]
	v_mfma_f32_16x16x32_bf16 v[32:35], v[152:155], v[178:181], v[32:35]
	v_mfma_f32_16x16x32_bf16 v[32:35], v[166:169], v[182:185], v[32:35]
	v_mfma_f32_16x16x32_bf16 v[16:19], v[152:155], v[186:189], v[16:19]
	v_mfma_f32_16x16x32_bf16 v[16:19], v[166:169], v[190:193], v[16:19]
	v_mfma_f32_16x16x32_bf16 v[0:3], v[152:155], v[200:203], v[0:3]
	v_mfma_f32_16x16x32_bf16 v[0:3], v[166:169], v[204:207], v[0:3]
	s_barrier
	s_add_i32 s96, s96, 2
	s_add_u32 s94, s94, 0x100
	s_addc_u32 s95, s95, 0
	s_cmpk_gt_u32 s96, 0x55
	s_mov_b64 s[18:19], s[22:23]
	s_cbranch_scc0 .LBB0_560
	s_branch .Lzexit_1

.LBB0_826:
	s_ashr_i32 s17, s16, 31
	s_lshl_b64 s[18:19], s[16:17], 20
	s_add_u32 s18, s41, s18
	s_addc_u32 s19, s45, s19
	s_and_b64 s[22:23], s[4:5], exec
	s_cselect_b32 s7, s19, s53
	s_cselect_b32 s17, s18, s52
	s_ashr_i32 s15, s14, 31
	s_lshl_b64 s[22:23], s[14:15], 20
	s_add_u32 s22, s65, s22
	s_addc_u32 s23, s85, s23
	s_and_b64 s[54:55], s[4:5], exec
	s_cselect_b32 s15, s23, s91
	s_cselect_b32 vcc_lo, s22, s90
	s_add_u32 s88, s52, 0x80080
	s_addc_u32 s89, s53, 0
	s_add_u32 s90, s90, 0x100
	v_mov_b32_e32 v0, 0
	s_addc_u32 s91, s91, 0
	s_mov_b32 vcc_hi, -2
	s_add_u32 s52, s88, 0xfff80080
	s_addc_u32 s53, s89, -1
	s_add_i32 s58, 0, 0x10000
	s_cmp_eq_u32 vcc_hi, 28
	s_cselect_b32 s55, s7, s53
	s_cselect_b32 s54, s17, s52
	s_cselect_b32 s53, s15, s91
	s_cselect_b32 s52, vcc_lo, s90
	s_add_i32 s81, 0, 0x14000
	v_add_u32_e32 v140, s58, v197
	v_add_u32_e32 v156, s81, v197
	ds_read_b128 v[128:131], v140
	ds_read_b128 v[132:135], v140 offset:1024
	ds_read_b128 v[136:139], v140 offset:2048
	ds_read_b128 v[140:143], v140 offset:3072
	ds_read_b128 v[144:147], v156
	ds_read_b128 v[148:151], v156 offset:1024
	ds_read_b128 v[152:155], v156 offset:2048
	ds_read_b128 v[156:159], v156 offset:3072
	v_lshl_add_u64 v[198:199], s[88:89], 0, v[192:193]
	s_add_i32 m0, s76, 0xc000
	ds_read_b128 v[160:163], v203
	ds_read_b128 v[164:167], v203 offset:1024
	ds_read_b128 v[168:171], v203 offset:2048
	ds_read_b128 v[172:175], v203 offset:3072
	ds_read_b128 v[204:207], v203 offset:4096
	ds_read_b128 v[208:211], v203 offset:5120
	ds_read_b128 v[212:215], v203 offset:6144
	ds_read_b128 v[218:221], v203 offset:7168
	global_load_lds_dwordx4 v[198:199], off
	v_lshl_add_u64 v[198:199], s[88:89], 0, v[194:195]
	s_add_i32 m0, s76, 0xe000
	s_nop 0
	global_load_lds_dwordx4 v[198:199], off
	s_waitcnt vmcnt(8)
	s_waitcnt lgkmcnt(0)
	s_barrier
	v_mfma_f32_16x16x32_bf16 v[124:127], v[128:131], v[160:163], 0
	v_mfma_f32_16x16x32_bf16 v[124:127], v[132:135], v[164:167], v[124:127]
	v_mfma_f32_16x16x32_bf16 v[108:111], v[128:131], v[168:171], 0
	v_mfma_f32_16x16x32_bf16 v[108:111], v[132:135], v[172:175], v[108:111]
	v_mfma_f32_16x16x32_bf16 v[92:95], v[128:131], v[204:207], 0
	v_mfma_f32_16x16x32_bf16 v[92:95], v[132:135], v[208:211], v[92:95]
	v_mfma_f32_16x16x32_bf16 v[76:79], v[128:131], v[212:215], 0
	v_mfma_f32_16x16x32_bf16 v[76:79], v[132:135], v[218:221], v[76:79]
	v_mfma_f32_16x16x32_bf16 v[120:123], v[136:139], v[160:163], 0
	v_mfma_f32_16x16x32_bf16 v[120:123], v[140:143], v[164:167], v[120:123]
	v_mfma_f32_16x16x32_bf16 v[104:107], v[136:139], v[168:171], 0
	v_mfma_f32_16x16x32_bf16 v[104:107], v[140:143], v[172:175], v[104:107]
	v_mfma_f32_16x16x32_bf16 v[88:91], v[136:139], v[204:207], 0
	v_mfma_f32_16x16x32_bf16 v[88:91], v[140:143], v[208:211], v[88:91]
	v_mfma_f32_16x16x32_bf16 v[72:75], v[136:139], v[212:215], 0
	v_mfma_f32_16x16x32_bf16 v[72:75], v[140:143], v[218:221], v[72:75]
	v_mfma_f32_16x16x32_bf16 v[116:119], v[144:147], v[160:163], 0
	v_mfma_f32_16x16x32_bf16 v[116:119], v[148:151], v[164:167], v[116:119]
	v_mfma_f32_16x16x32_bf16 v[100:103], v[144:147], v[168:171], 0
	v_mfma_f32_16x16x32_bf16 v[100:103], v[148:151], v[172:175], v[100:103]
	v_mfma_f32_16x16x32_bf16 v[84:87], v[144:147], v[204:207], 0
	v_mfma_f32_16x16x32_bf16 v[84:87], v[148:151], v[208:211], v[84:87]
	v_mfma_f32_16x16x32_bf16 v[68:71], v[144:147], v[212:215], 0
	v_mfma_f32_16x16x32_bf16 v[68:71], v[148:151], v[218:221], v[68:71]
	v_mfma_f32_16x16x32_bf16 v[112:115], v[152:155], v[160:163], 0
	v_mfma_f32_16x16x32_bf16 v[112:115], v[156:159], v[164:167], v[112:115]
	v_mfma_f32_16x16x32_bf16 v[96:99], v[152:155], v[168:171], 0
	v_mfma_f32_16x16x32_bf16 v[96:99], v[156:159], v[172:175], v[96:99]
	v_mfma_f32_16x16x32_bf16 v[80:83], v[152:155], v[204:207], 0
	v_mfma_f32_16x16x32_bf16 v[80:83], v[156:159], v[208:211], v[80:83]
	v_mfma_f32_16x16x32_bf16 v[64:67], v[152:155], v[212:215], 0
	v_mfma_f32_16x16x32_bf16 v[64:67], v[156:159], v[218:221], v[64:67]
	s_barrier
	s_add_i32 s58, s58, s50
	v_lshl_add_u64 v[198:199], s[52:53], 0, v[178:179]
	s_mov_b32 m0, s58
	ds_read_b128 v[160:163], v203 offset:16384
	ds_read_b128 v[164:167], v203 offset:17408
	ds_read_b128 v[168:171], v203 offset:18432
	ds_read_b128 v[172:175], v203 offset:19456
	ds_read_b128 v[204:207], v203 offset:20480
	ds_read_b128 v[208:211], v203 offset:21504
	ds_read_b128 v[212:215], v203 offset:22528
	ds_read_b128 v[218:221], v203 offset:23552
	global_load_lds_dwordx4 v[198:199], off
	s_add_i32 m0, s58, 0x2000
	s_add_u32 s58, s52, 0x80000
	v_lshl_add_u64 v[222:223], s[52:53], 0, v[182:183]
	s_addc_u32 s59, s53, 0
	s_add_i32 s81, s81, s50
	global_load_lds_dwordx4 v[222:223], off
	v_lshl_add_u64 v[224:225], s[58:59], 0, v[178:179]
	s_mov_b32 m0, s81
	v_lshl_add_u64 v[226:227], s[54:55], 0, v[180:181]
	global_load_lds_dwordx4 v[224:225], off
	v_lshl_add_u64 v[224:225], s[58:59], 0, v[182:183]
	s_add_i32 m0, s81, 0x2000
	s_nop 0
	global_load_lds_dwordx4 v[224:225], off
	v_lshl_add_u64 v[224:225], s[54:55], 0, v[176:177]
	s_mov_b32 m0, s76
	s_nop 0
	global_load_lds_dwordx4 v[224:225], off
	s_mov_b32 m0, s87
	s_nop 0
	global_load_lds_dwordx4 v[226:227], off
	s_waitcnt vmcnt(8)
	s_waitcnt lgkmcnt(0)
	s_barrier
	v_mfma_f32_16x16x32_bf16 v[60:63], v[128:131], v[160:163], 0
	v_mfma_f32_16x16x32_bf16 v[60:63], v[132:135], v[164:167], v[60:63]
	v_mfma_f32_16x16x32_bf16 v[44:47], v[128:131], v[168:171], 0
	v_mfma_f32_16x16x32_bf16 v[44:47], v[132:135], v[172:175], v[44:47]
	v_mfma_f32_16x16x32_bf16 v[28:31], v[128:131], v[204:207], 0
	v_mfma_f32_16x16x32_bf16 v[28:31], v[132:135], v[208:211], v[28:31]
	v_mfma_f32_16x16x32_bf16 v[12:15], v[128:131], v[212:215], 0
	v_mfma_f32_16x16x32_bf16 v[12:15], v[132:135], v[218:221], v[12:15]
	v_mfma_f32_16x16x32_bf16 v[56:59], v[136:139], v[160:163], 0
	v_mfma_f32_16x16x32_bf16 v[56:59], v[140:143], v[164:167], v[56:59]
	v_mfma_f32_16x16x32_bf16 v[40:43], v[136:139], v[168:171], 0
	v_mfma_f32_16x16x32_bf16 v[40:43], v[140:143], v[172:175], v[40:43]
	v_mfma_f32_16x16x32_bf16 v[24:27], v[136:139], v[204:207], 0
	v_mfma_f32_16x16x32_bf16 v[24:27], v[140:143], v[208:211], v[24:27]
	v_mfma_f32_16x16x32_bf16 v[8:11], v[136:139], v[212:215], 0
	v_mfma_f32_16x16x32_bf16 v[8:11], v[140:143], v[218:221], v[8:11]
	v_mfma_f32_16x16x32_bf16 v[52:55], v[144:147], v[160:163], 0
	v_mfma_f32_16x16x32_bf16 v[52:55], v[148:151], v[164:167], v[52:55]
	v_mfma_f32_16x16x32_bf16 v[36:39], v[144:147], v[168:171], 0
	v_mfma_f32_16x16x32_bf16 v[36:39], v[148:151], v[172:175], v[36:39]
	v_mfma_f32_16x16x32_bf16 v[20:23], v[144:147], v[204:207], 0
	v_mfma_f32_16x16x32_bf16 v[20:23], v[148:151], v[208:211], v[20:23]
	v_mfma_f32_16x16x32_bf16 v[4:7], v[144:147], v[212:215], 0
	v_mfma_f32_16x16x32_bf16 v[4:7], v[148:151], v[218:221], v[4:7]
	v_mfma_f32_16x16x32_bf16 v[48:51], v[152:155], v[160:163], 0
	v_mfma_f32_16x16x32_bf16 v[48:51], v[156:159], v[164:167], v[48:51]
	v_mfma_f32_16x16x32_bf16 v[32:35], v[152:155], v[168:171], 0
	v_mfma_f32_16x16x32_bf16 v[32:35], v[156:159], v[172:175], v[32:35]
	v_mfma_f32_16x16x32_bf16 v[16:19], v[152:155], v[204:207], 0
	v_mfma_f32_16x16x32_bf16 v[16:19], v[156:159], v[208:211], v[16:19]
	v_mfma_f32_16x16x32_bf16 v[0:3], v[152:155], v[212:215], 0
	v_mfma_f32_16x16x32_bf16 v[0:3], v[156:159], v[218:221], v[0:3]
	s_barrier
	s_add_i32 s58, 0, 0x18000
	s_add_i32 s59, 0, 0x1c000
	v_add_u32_e32 v140, s58, v197
	v_add_u32_e32 v156, s59, v197
	ds_read_b128 v[128:131], v140
	ds_read_b128 v[132:135], v140 offset:1024
	ds_read_b128 v[136:139], v140 offset:2048
	ds_read_b128 v[140:143], v140 offset:3072
	ds_read_b128 v[144:147], v156
	ds_read_b128 v[148:151], v156 offset:1024
	ds_read_b128 v[152:155], v156 offset:2048
	ds_read_b128 v[156:159], v156 offset:3072
	s_add_u32 s54, s54, 0x80000
	s_addc_u32 s55, s55, 0
	s_mov_b32 m0, s92
	v_lshl_add_u64 v[228:229], s[54:55], 0, v[176:177]
	ds_read_b128 v[160:163], v203 offset:32768
	ds_read_b128 v[164:167], v203 offset:33792
	ds_read_b128 v[168:171], v203 offset:34816
	ds_read_b128 v[172:175], v203 offset:35840
	ds_read_b128 v[204:207], v203 offset:36864
	ds_read_b128 v[208:211], v203 offset:37888
	ds_read_b128 v[212:215], v203 offset:38912
	ds_read_b128 v[218:221], v203 offset:39936
	global_load_lds_dwordx4 v[228:229], off
	v_lshl_add_u64 v[228:229], s[54:55], 0, v[180:181]
	s_mov_b32 m0, s93
	s_nop 0
	global_load_lds_dwordx4 v[228:229], off
	s_waitcnt vmcnt(8)
	s_waitcnt lgkmcnt(0)
	s_barrier
	v_mfma_f32_16x16x32_bf16 v[124:127], v[128:131], v[160:163], v[124:127]
	v_mfma_f32_16x16x32_bf16 v[124:127], v[132:135], v[164:167], v[124:127]
	v_mfma_f32_16x16x32_bf16 v[108:111], v[128:131], v[168:171], v[108:111]
	v_mfma_f32_16x16x32_bf16 v[108:111], v[132:135], v[172:175], v[108:111]
	v_mfma_f32_16x16x32_bf16 v[92:95], v[128:131], v[204:207], v[92:95]
	v_mfma_f32_16x16x32_bf16 v[92:95], v[132:135], v[208:211], v[92:95]
	v_mfma_f32_16x16x32_bf16 v[76:79], v[128:131], v[212:215], v[76:79]
	v_mfma_f32_16x16x32_bf16 v[76:79], v[132:135], v[218:221], v[76:79]
	v_mfma_f32_16x16x32_bf16 v[120:123], v[136:139], v[160:163], v[120:123]
	v_mfma_f32_16x16x32_bf16 v[120:123], v[140:143], v[164:167], v[120:123]
	v_mfma_f32_16x16x32_bf16 v[104:107], v[136:139], v[168:171], v[104:107]
	v_mfma_f32_16x16x32_bf16 v[104:107], v[140:143], v[172:175], v[104:107]
	v_mfma_f32_16x16x32_bf16 v[88:91], v[136:139], v[204:207], v[88:91]
	v_mfma_f32_16x16x32_bf16 v[88:91], v[140:143], v[208:211], v[88:91]
	v_mfma_f32_16x16x32_bf16 v[72:75], v[136:139], v[212:215], v[72:75]
	v_mfma_f32_16x16x32_bf16 v[72:75], v[140:143], v[218:221], v[72:75]
	v_mfma_f32_16x16x32_bf16 v[116:119], v[144:147], v[160:163], v[116:119]
	v_mfma_f32_16x16x32_bf16 v[116:119], v[148:151], v[164:167], v[116:119]
	v_mfma_f32_16x16x32_bf16 v[100:103], v[144:147], v[168:171], v[100:103]
	v_mfma_f32_16x16x32_bf16 v[100:103], v[148:151], v[172:175], v[100:103]
	v_mfma_f32_16x16x32_bf16 v[84:87], v[144:147], v[204:207], v[84:87]
	v_mfma_f32_16x16x32_bf16 v[84:87], v[148:151], v[208:211], v[84:87]
	v_mfma_f32_16x16x32_bf16 v[68:71], v[144:147], v[212:215], v[68:71]
	v_mfma_f32_16x16x32_bf16 v[68:71], v[148:151], v[218:221], v[68:71]
	v_mfma_f32_16x16x32_bf16 v[112:115], v[152:155], v[160:163], v[112:115]
	v_mfma_f32_16x16x32_bf16 v[112:115], v[156:159], v[164:167], v[112:115]
	v_mfma_f32_16x16x32_bf16 v[96:99], v[152:155], v[168:171], v[96:99]
	v_mfma_f32_16x16x32_bf16 v[96:99], v[156:159], v[172:175], v[96:99]
	v_mfma_f32_16x16x32_bf16 v[80:83], v[152:155], v[204:207], v[80:83]
	v_mfma_f32_16x16x32_bf16 v[80:83], v[156:159], v[208:211], v[80:83]
	v_mfma_f32_16x16x32_bf16 v[64:67], v[152:155], v[212:215], v[64:67]
	v_mfma_f32_16x16x32_bf16 v[64:67], v[156:159], v[218:221], v[64:67]
	s_barrier
	s_add_i32 s54, s58, s50
	v_lshl_add_u64 v[198:199], v[198:199], 0, s[60:61]
	s_mov_b32 m0, s54
	ds_read_b128 v[160:163], v203 offset:49152
	ds_read_b128 v[164:167], v203 offset:50176
	ds_read_b128 v[168:171], v203 offset:51200
	ds_read_b128 v[172:175], v203 offset:52224
	ds_read_b128 v[204:207], v203 offset:53248
	ds_read_b128 v[208:211], v203 offset:54272
	ds_read_b128 v[212:215], v203 offset:55296
	ds_read_b128 v[218:221], v203 offset:56320
	global_load_lds_dwordx4 v[198:199], off
	s_add_i32 m0, s54, 0x2000
	s_add_u32 s52, s52, 0x80080
	v_lshl_add_u64 v[198:199], v[222:223], 0, s[60:61]
	s_addc_u32 s53, s53, 0
	s_add_i32 s54, s59, s50
	global_load_lds_dwordx4 v[198:199], off
	v_lshl_add_u64 v[198:199], s[52:53], 0, v[178:179]
	s_mov_b32 m0, s54
	s_nop 0
	global_load_lds_dwordx4 v[198:199], off
	v_lshl_add_u64 v[198:199], s[52:53], 0, v[182:183]
	s_add_i32 m0, s54, 0x2000
	s_nop 0
	global_load_lds_dwordx4 v[198:199], off
	v_lshl_add_u64 v[198:199], v[224:225], 0, s[60:61]
	s_mov_b32 m0, s94
	s_nop 0
	global_load_lds_dwordx4 v[198:199], off
	v_lshl_add_u64 v[198:199], v[226:227], 0, s[60:61]
	s_mov_b32 m0, s95
	s_nop 0
	global_load_lds_dwordx4 v[198:199], off
	s_waitcnt vmcnt(8)
	s_waitcnt lgkmcnt(0)
	s_barrier
	v_mfma_f32_16x16x32_bf16 v[60:63], v[128:131], v[160:163], v[60:63]
	v_mfma_f32_16x16x32_bf16 v[60:63], v[132:135], v[164:167], v[60:63]
	v_mfma_f32_16x16x32_bf16 v[44:47], v[128:131], v[168:171], v[44:47]
	v_mfma_f32_16x16x32_bf16 v[44:47], v[132:135], v[172:175], v[44:47]
	v_mfma_f32_16x16x32_bf16 v[28:31], v[128:131], v[204:207], v[28:31]
	v_mfma_f32_16x16x32_bf16 v[28:31], v[132:135], v[208:211], v[28:31]
	v_mfma_f32_16x16x32_bf16 v[12:15], v[128:131], v[212:215], v[12:15]
	v_mfma_f32_16x16x32_bf16 v[12:15], v[132:135], v[218:221], v[12:15]
	v_mfma_f32_16x16x32_bf16 v[56:59], v[136:139], v[160:163], v[56:59]
	v_mfma_f32_16x16x32_bf16 v[56:59], v[140:143], v[164:167], v[56:59]
	v_mfma_f32_16x16x32_bf16 v[40:43], v[136:139], v[168:171], v[40:43]
	v_mfma_f32_16x16x32_bf16 v[40:43], v[140:143], v[172:175], v[40:43]
	v_mfma_f32_16x16x32_bf16 v[24:27], v[136:139], v[204:207], v[24:27]
	v_mfma_f32_16x16x32_bf16 v[24:27], v[140:143], v[208:211], v[24:27]
	v_mfma_f32_16x16x32_bf16 v[8:11], v[136:139], v[212:215], v[8:11]
	v_mfma_f32_16x16x32_bf16 v[8:11], v[140:143], v[218:221], v[8:11]
	v_mfma_f32_16x16x32_bf16 v[52:55], v[144:147], v[160:163], v[52:55]
	v_mfma_f32_16x16x32_bf16 v[52:55], v[148:151], v[164:167], v[52:55]
	v_mfma_f32_16x16x32_bf16 v[36:39], v[144:147], v[168:171], v[36:39]
	v_mfma_f32_16x16x32_bf16 v[36:39], v[148:151], v[172:175], v[36:39]
	v_mfma_f32_16x16x32_bf16 v[20:23], v[144:147], v[204:207], v[20:23]
	v_mfma_f32_16x16x32_bf16 v[20:23], v[148:151], v[208:211], v[20:23]
	v_mfma_f32_16x16x32_bf16 v[4:7], v[144:147], v[212:215], v[4:7]
	v_mfma_f32_16x16x32_bf16 v[4:7], v[148:151], v[218:221], v[4:7]
	v_mfma_f32_16x16x32_bf16 v[48:51], v[152:155], v[160:163], v[48:51]
	v_mfma_f32_16x16x32_bf16 v[48:51], v[156:159], v[164:167], v[48:51]
	v_mfma_f32_16x16x32_bf16 v[32:35], v[152:155], v[168:171], v[32:35]
	v_mfma_f32_16x16x32_bf16 v[32:35], v[156:159], v[172:175], v[32:35]
	v_mfma_f32_16x16x32_bf16 v[16:19], v[152:155], v[204:207], v[16:19]
	v_mfma_f32_16x16x32_bf16 v[16:19], v[156:159], v[208:211], v[16:19]
	v_mfma_f32_16x16x32_bf16 v[0:3], v[152:155], v[212:215], v[0:3]
	v_mfma_f32_16x16x32_bf16 v[0:3], v[156:159], v[218:221], v[0:3]
	s_barrier
	s_add_i32 vcc_hi, vcc_hi, 2
	s_add_u32 s88, s88, 0x100
	s_addc_u32 s89, s89, 0
	s_add_u32 s90, s90, 0x100
	s_addc_u32 s91, s91, 0
	s_cmp_gt_u32 vcc_hi, 29
	s_cbranch_scc0 .LBB0_827
	s_branch .Lzexit_2

.LBB0_1008:
	s_lshl_b64 s[2:3], s[8:9], 18
	s_add_u32 s7, s41, s2
	s_addc_u32 s9, s42, s3
	s_and_b64 s[2:3], s[10:11], exec
	s_cselect_b32 s15, s9, s19
	s_cselect_b32 s14, s7, s18
	s_add_u32 s7, s18, 0x100
	v_mov_b32_e32 v0, 0
	s_addc_u32 s9, s19, 0
	s_mov_b32 s93, -2
	s_add_u32 s18, s16, 0x100
	s_addc_u32 s19, s17, 0
	s_add_i32 s2, 0, 0x10000
	s_cmp_eq_u32 s93, 4
	s_cselect_b32 s53, s13, s19
	s_cselect_b32 s52, s12, s18
	s_cselect_b32 s23, s15, s9
	s_cselect_b32 s22, s14, s7
	s_add_i32 s58, 0, 0x14000
	v_add_u32_e32 v156, s2, v142
	v_add_u32_e32 v172, s58, v142
	ds_read_b128 v[144:147], v156
	ds_read_b128 v[148:151], v156 offset:1024
	ds_read_b128 v[152:155], v156 offset:2048
	ds_read_b128 v[156:159], v156 offset:3072
	ds_read_b128 v[160:163], v172
	ds_read_b128 v[164:167], v172 offset:1024
	ds_read_b128 v[168:171], v172 offset:2048
	ds_read_b128 v[172:175], v172 offset:3072
	v_lshl_add_u64 v[208:209], s[16:17], 0, v[136:137]
	s_add_i32 m0, s76, 0xc000
	ds_read_b128 v[176:179], v143
	ds_read_b128 v[180:183], v143 offset:1024
	ds_read_b128 v[184:187], v143 offset:2048
	ds_read_b128 v[188:191], v143 offset:3072
	ds_read_b128 v[192:195], v143 offset:4096
	ds_read_b128 v[196:199], v143 offset:5120
	ds_read_b128 v[200:203], v143 offset:6144
	ds_read_b128 v[204:207], v143 offset:7168
	global_load_lds_dwordx4 v[208:209], off
	v_lshl_add_u64 v[208:209], s[16:17], 0, v[138:139]
	s_add_i32 m0, s76, 0xe000
	s_nop 0
	global_load_lds_dwordx4 v[208:209], off
	s_waitcnt vmcnt(8)
	s_waitcnt lgkmcnt(0)
	s_barrier
	v_mfma_f32_16x16x32_bf16 v[124:127], v[144:147], v[176:179], 0
	v_mfma_f32_16x16x32_bf16 v[124:127], v[148:151], v[180:183], v[124:127]
	v_mfma_f32_16x16x32_bf16 v[116:119], v[144:147], v[184:187], 0
	v_mfma_f32_16x16x32_bf16 v[116:119], v[148:151], v[188:191], v[116:119]
	v_mfma_f32_16x16x32_bf16 v[104:107], v[144:147], v[192:195], 0
	v_mfma_f32_16x16x32_bf16 v[104:107], v[148:151], v[196:199], v[104:107]
	v_mfma_f32_16x16x32_bf16 v[88:91], v[144:147], v[200:203], 0
	v_mfma_f32_16x16x32_bf16 v[88:91], v[148:151], v[204:207], v[88:91]
	v_mfma_f32_16x16x32_bf16 v[120:123], v[152:155], v[176:179], 0
	v_mfma_f32_16x16x32_bf16 v[120:123], v[156:159], v[180:183], v[120:123]
	v_mfma_f32_16x16x32_bf16 v[112:115], v[152:155], v[184:187], 0
	v_mfma_f32_16x16x32_bf16 v[112:115], v[156:159], v[188:191], v[112:115]
	v_mfma_f32_16x16x32_bf16 v[96:99], v[152:155], v[192:195], 0
	v_mfma_f32_16x16x32_bf16 v[96:99], v[156:159], v[196:199], v[96:99]
	v_mfma_f32_16x16x32_bf16 v[80:83], v[152:155], v[200:203], 0
	v_mfma_f32_16x16x32_bf16 v[80:83], v[156:159], v[204:207], v[80:83]
	v_mfma_f32_16x16x32_bf16 v[108:111], v[160:163], v[176:179], 0
	v_mfma_f32_16x16x32_bf16 v[108:111], v[164:167], v[180:183], v[108:111]
	v_mfma_f32_16x16x32_bf16 v[92:95], v[160:163], v[184:187], 0
	v_mfma_f32_16x16x32_bf16 v[92:95], v[164:167], v[188:191], v[92:95]
	v_mfma_f32_16x16x32_bf16 v[76:79], v[160:163], v[192:195], 0
	v_mfma_f32_16x16x32_bf16 v[76:79], v[164:167], v[196:199], v[76:79]
	v_mfma_f32_16x16x32_bf16 v[68:71], v[160:163], v[200:203], 0
	v_mfma_f32_16x16x32_bf16 v[68:71], v[164:167], v[204:207], v[68:71]
	v_mfma_f32_16x16x32_bf16 v[100:103], v[168:171], v[176:179], 0
	v_mfma_f32_16x16x32_bf16 v[100:103], v[172:175], v[180:183], v[100:103]
	v_mfma_f32_16x16x32_bf16 v[84:87], v[168:171], v[184:187], 0
	v_mfma_f32_16x16x32_bf16 v[84:87], v[172:175], v[188:191], v[84:87]
	v_mfma_f32_16x16x32_bf16 v[72:75], v[168:171], v[192:195], 0
	v_mfma_f32_16x16x32_bf16 v[72:75], v[172:175], v[196:199], v[72:75]
	v_mfma_f32_16x16x32_bf16 v[64:67], v[168:171], v[200:203], 0
	v_mfma_f32_16x16x32_bf16 v[64:67], v[172:175], v[204:207], v[64:67]
	s_barrier
	s_add_i32 s2, s2, s50
	v_lshl_add_u64 v[208:209], s[22:23], 0, v[216:217]
	s_mov_b32 m0, s2
	ds_read_b128 v[176:179], v143 offset:16384
	ds_read_b128 v[180:183], v143 offset:17408
	ds_read_b128 v[184:187], v143 offset:18432
	ds_read_b128 v[188:191], v143 offset:19456
	ds_read_b128 v[192:195], v143 offset:20480
	ds_read_b128 v[196:199], v143 offset:21504
	ds_read_b128 v[200:203], v143 offset:22528
	ds_read_b128 v[204:207], v143 offset:23552
	global_load_lds_dwordx4 v[208:209], off
	s_add_i32 m0, s2, 0x2000
	s_add_u32 s2, s22, 0x20000
	v_lshl_add_u64 v[210:211], s[22:23], 0, v[128:129]
	s_addc_u32 s3, s23, 0
	s_add_i32 s16, s58, s50
	global_load_lds_dwordx4 v[210:211], off
	v_lshl_add_u64 v[212:213], s[2:3], 0, v[216:217]
	s_mov_b32 m0, s16
	v_lshl_add_u64 v[214:215], s[52:53], 0, v[130:131]
	global_load_lds_dwordx4 v[212:213], off
	v_lshl_add_u64 v[212:213], s[2:3], 0, v[128:129]
	s_add_i32 m0, s16, 0x2000
	s_nop 0
	global_load_lds_dwordx4 v[212:213], off
	v_lshl_add_u64 v[212:213], s[52:53], 0, v[132:133]
	s_mov_b32 m0, s76
	s_nop 0
	global_load_lds_dwordx4 v[212:213], off
	s_mov_b32 m0, s72
	s_nop 0
	global_load_lds_dwordx4 v[214:215], off
	s_waitcnt vmcnt(8)
	s_waitcnt lgkmcnt(0)
	s_barrier
	v_mfma_f32_16x16x32_bf16 v[60:63], v[144:147], v[176:179], 0
	v_mfma_f32_16x16x32_bf16 v[60:63], v[148:151], v[180:183], v[60:63]
	v_mfma_f32_16x16x32_bf16 v[52:55], v[144:147], v[184:187], 0
	v_mfma_f32_16x16x32_bf16 v[52:55], v[148:151], v[188:191], v[52:55]
	v_mfma_f32_16x16x32_bf16 v[36:39], v[144:147], v[192:195], 0
	v_mfma_f32_16x16x32_bf16 v[36:39], v[148:151], v[196:199], v[36:39]
	v_mfma_f32_16x16x32_bf16 v[20:23], v[144:147], v[200:203], 0
	v_mfma_f32_16x16x32_bf16 v[20:23], v[148:151], v[204:207], v[20:23]
	v_mfma_f32_16x16x32_bf16 v[56:59], v[152:155], v[176:179], 0
	v_mfma_f32_16x16x32_bf16 v[56:59], v[156:159], v[180:183], v[56:59]
	v_mfma_f32_16x16x32_bf16 v[48:51], v[152:155], v[184:187], 0
	v_mfma_f32_16x16x32_bf16 v[48:51], v[156:159], v[188:191], v[48:51]
	v_mfma_f32_16x16x32_bf16 v[32:35], v[152:155], v[192:195], 0
	v_mfma_f32_16x16x32_bf16 v[32:35], v[156:159], v[196:199], v[32:35]
	v_mfma_f32_16x16x32_bf16 v[16:19], v[152:155], v[200:203], 0
	v_mfma_f32_16x16x32_bf16 v[16:19], v[156:159], v[204:207], v[16:19]
	v_mfma_f32_16x16x32_bf16 v[44:47], v[160:163], v[176:179], 0
	v_mfma_f32_16x16x32_bf16 v[44:47], v[164:167], v[180:183], v[44:47]
	v_mfma_f32_16x16x32_bf16 v[28:31], v[160:163], v[184:187], 0
	v_mfma_f32_16x16x32_bf16 v[28:31], v[164:167], v[188:191], v[28:31]
	v_mfma_f32_16x16x32_bf16 v[12:15], v[160:163], v[192:195], 0
	v_mfma_f32_16x16x32_bf16 v[12:15], v[164:167], v[196:199], v[12:15]
	v_mfma_f32_16x16x32_bf16 v[4:7], v[160:163], v[200:203], 0
	v_mfma_f32_16x16x32_bf16 v[4:7], v[164:167], v[204:207], v[4:7]
	v_mfma_f32_16x16x32_bf16 v[40:43], v[168:171], v[176:179], 0
	v_mfma_f32_16x16x32_bf16 v[40:43], v[172:175], v[180:183], v[40:43]
	v_mfma_f32_16x16x32_bf16 v[24:27], v[168:171], v[184:187], 0
	v_mfma_f32_16x16x32_bf16 v[24:27], v[172:175], v[188:191], v[24:27]
	v_mfma_f32_16x16x32_bf16 v[8:11], v[168:171], v[192:195], 0
	v_mfma_f32_16x16x32_bf16 v[8:11], v[172:175], v[196:199], v[8:11]
	v_mfma_f32_16x16x32_bf16 v[0:3], v[168:171], v[200:203], 0
	v_mfma_f32_16x16x32_bf16 v[0:3], v[172:175], v[204:207], v[0:3]
	s_barrier
	s_add_i32 s16, 0, 0x18000
	s_add_i32 s17, 0, 0x1c000
	v_add_u32_e32 v156, s16, v142
	v_add_u32_e32 v172, s17, v142
	ds_read_b128 v[144:147], v156
	ds_read_b128 v[148:151], v156 offset:1024
	ds_read_b128 v[152:155], v156 offset:2048
	ds_read_b128 v[156:159], v156 offset:3072
	ds_read_b128 v[160:163], v172
	ds_read_b128 v[164:167], v172 offset:1024
	ds_read_b128 v[168:171], v172 offset:2048
	ds_read_b128 v[172:175], v172 offset:3072
	s_add_u32 s2, s52, 0x30000
	s_addc_u32 s3, s53, 0
	s_mov_b32 m0, s74
	v_lshl_add_u64 v[218:219], s[2:3], 0, v[132:133]
	ds_read_b128 v[176:179], v143 offset:32768
	ds_read_b128 v[180:183], v143 offset:33792
	ds_read_b128 v[184:187], v143 offset:34816
	ds_read_b128 v[188:191], v143 offset:35840
	ds_read_b128 v[192:195], v143 offset:36864
	ds_read_b128 v[196:199], v143 offset:37888
	ds_read_b128 v[200:203], v143 offset:38912
	ds_read_b128 v[204:207], v143 offset:39936
	global_load_lds_dwordx4 v[218:219], off
	v_lshl_add_u64 v[218:219], s[2:3], 0, v[130:131]
	s_mov_b32 m0, s85
	s_nop 0
	global_load_lds_dwordx4 v[218:219], off
	s_waitcnt vmcnt(8)
	s_waitcnt lgkmcnt(0)
	s_barrier
	v_mfma_f32_16x16x32_bf16 v[124:127], v[144:147], v[176:179], v[124:127]
	v_mfma_f32_16x16x32_bf16 v[124:127], v[148:151], v[180:183], v[124:127]
	v_mfma_f32_16x16x32_bf16 v[116:119], v[144:147], v[184:187], v[116:119]
	v_mfma_f32_16x16x32_bf16 v[116:119], v[148:151], v[188:191], v[116:119]
	v_mfma_f32_16x16x32_bf16 v[104:107], v[144:147], v[192:195], v[104:107]
	v_mfma_f32_16x16x32_bf16 v[104:107], v[148:151], v[196:199], v[104:107]
	v_mfma_f32_16x16x32_bf16 v[88:91], v[144:147], v[200:203], v[88:91]
	v_mfma_f32_16x16x32_bf16 v[88:91], v[148:151], v[204:207], v[88:91]
	v_mfma_f32_16x16x32_bf16 v[120:123], v[152:155], v[176:179], v[120:123]
	v_mfma_f32_16x16x32_bf16 v[120:123], v[156:159], v[180:183], v[120:123]
	v_mfma_f32_16x16x32_bf16 v[112:115], v[152:155], v[184:187], v[112:115]
	v_mfma_f32_16x16x32_bf16 v[112:115], v[156:159], v[188:191], v[112:115]
	v_mfma_f32_16x16x32_bf16 v[96:99], v[152:155], v[192:195], v[96:99]
	v_mfma_f32_16x16x32_bf16 v[96:99], v[156:159], v[196:199], v[96:99]
	v_mfma_f32_16x16x32_bf16 v[80:83], v[152:155], v[200:203], v[80:83]
	v_mfma_f32_16x16x32_bf16 v[80:83], v[156:159], v[204:207], v[80:83]
	v_mfma_f32_16x16x32_bf16 v[108:111], v[160:163], v[176:179], v[108:111]
	v_mfma_f32_16x16x32_bf16 v[108:111], v[164:167], v[180:183], v[108:111]
	v_mfma_f32_16x16x32_bf16 v[92:95], v[160:163], v[184:187], v[92:95]
	v_mfma_f32_16x16x32_bf16 v[92:95], v[164:167], v[188:191], v[92:95]
	v_mfma_f32_16x16x32_bf16 v[76:79], v[160:163], v[192:195], v[76:79]
	v_mfma_f32_16x16x32_bf16 v[76:79], v[164:167], v[196:199], v[76:79]
	v_mfma_f32_16x16x32_bf16 v[68:71], v[160:163], v[200:203], v[68:71]
	v_mfma_f32_16x16x32_bf16 v[68:71], v[164:167], v[204:207], v[68:71]
	v_mfma_f32_16x16x32_bf16 v[100:103], v[168:171], v[176:179], v[100:103]
	v_mfma_f32_16x16x32_bf16 v[100:103], v[172:175], v[180:183], v[100:103]
	v_mfma_f32_16x16x32_bf16 v[84:87], v[168:171], v[184:187], v[84:87]
	v_mfma_f32_16x16x32_bf16 v[84:87], v[172:175], v[188:191], v[84:87]
	v_mfma_f32_16x16x32_bf16 v[72:75], v[168:171], v[192:195], v[72:75]
	v_mfma_f32_16x16x32_bf16 v[72:75], v[172:175], v[196:199], v[72:75]
	v_mfma_f32_16x16x32_bf16 v[64:67], v[168:171], v[200:203], v[64:67]
	v_mfma_f32_16x16x32_bf16 v[64:67], v[172:175], v[204:207], v[64:67]
	s_barrier
	s_add_i32 s2, s16, s50
	v_lshl_add_u64 v[208:209], v[208:209], 0, s[60:61]
	s_mov_b32 m0, s2
	ds_read_b128 v[176:179], v143 offset:49152
	ds_read_b128 v[180:183], v143 offset:50176
	ds_read_b128 v[184:187], v143 offset:51200
	ds_read_b128 v[188:191], v143 offset:52224
	ds_read_b128 v[192:195], v143 offset:53248
	ds_read_b128 v[196:199], v143 offset:54272
	ds_read_b128 v[200:203], v143 offset:55296
	ds_read_b128 v[204:207], v143 offset:56320
	global_load_lds_dwordx4 v[208:209], off
	s_add_i32 m0, s2, 0x2000
	s_add_u32 s2, s22, 0x20080
	v_lshl_add_u64 v[208:209], v[210:211], 0, s[60:61]
	s_addc_u32 s3, s23, 0
	s_add_i32 s16, s17, s50
	global_load_lds_dwordx4 v[208:209], off
	v_lshl_add_u64 v[208:209], s[2:3], 0, v[216:217]
	s_mov_b32 m0, s16
	s_nop 0
	global_load_lds_dwordx4 v[208:209], off
	v_lshl_add_u64 v[208:209], s[2:3], 0, v[128:129]
	s_add_i32 m0, s16, 0x2000
	s_nop 0
	global_load_lds_dwordx4 v[208:209], off
	v_lshl_add_u64 v[208:209], v[212:213], 0, s[60:61]
	s_mov_b32 m0, s89
	s_nop 0
	global_load_lds_dwordx4 v[208:209], off
	v_lshl_add_u64 v[208:209], v[214:215], 0, s[60:61]
	s_mov_b32 m0, s90
	s_nop 0
	global_load_lds_dwordx4 v[208:209], off
	s_waitcnt vmcnt(8)
	s_waitcnt lgkmcnt(0)
	s_barrier
	v_mfma_f32_16x16x32_bf16 v[60:63], v[144:147], v[176:179], v[60:63]
	v_mfma_f32_16x16x32_bf16 v[60:63], v[148:151], v[180:183], v[60:63]
	v_mfma_f32_16x16x32_bf16 v[52:55], v[144:147], v[184:187], v[52:55]
	v_mfma_f32_16x16x32_bf16 v[52:55], v[148:151], v[188:191], v[52:55]
	v_mfma_f32_16x16x32_bf16 v[36:39], v[144:147], v[192:195], v[36:39]
	v_mfma_f32_16x16x32_bf16 v[36:39], v[148:151], v[196:199], v[36:39]
	v_mfma_f32_16x16x32_bf16 v[20:23], v[144:147], v[200:203], v[20:23]
	v_mfma_f32_16x16x32_bf16 v[20:23], v[148:151], v[204:207], v[20:23]
	v_mfma_f32_16x16x32_bf16 v[56:59], v[152:155], v[176:179], v[56:59]
	v_mfma_f32_16x16x32_bf16 v[56:59], v[156:159], v[180:183], v[56:59]
	v_mfma_f32_16x16x32_bf16 v[48:51], v[152:155], v[184:187], v[48:51]
	v_mfma_f32_16x16x32_bf16 v[48:51], v[156:159], v[188:191], v[48:51]
	v_mfma_f32_16x16x32_bf16 v[32:35], v[152:155], v[192:195], v[32:35]
	v_mfma_f32_16x16x32_bf16 v[32:35], v[156:159], v[196:199], v[32:35]
	v_mfma_f32_16x16x32_bf16 v[16:19], v[152:155], v[200:203], v[16:19]
	v_mfma_f32_16x16x32_bf16 v[16:19], v[156:159], v[204:207], v[16:19]
	v_mfma_f32_16x16x32_bf16 v[44:47], v[160:163], v[176:179], v[44:47]
	v_mfma_f32_16x16x32_bf16 v[44:47], v[164:167], v[180:183], v[44:47]
	v_mfma_f32_16x16x32_bf16 v[28:31], v[160:163], v[184:187], v[28:31]
	v_mfma_f32_16x16x32_bf16 v[28:31], v[164:167], v[188:191], v[28:31]
	v_mfma_f32_16x16x32_bf16 v[12:15], v[160:163], v[192:195], v[12:15]
	v_mfma_f32_16x16x32_bf16 v[12:15], v[164:167], v[196:199], v[12:15]
	v_mfma_f32_16x16x32_bf16 v[4:7], v[160:163], v[200:203], v[4:7]
	v_mfma_f32_16x16x32_bf16 v[4:7], v[164:167], v[204:207], v[4:7]
	v_mfma_f32_16x16x32_bf16 v[40:43], v[168:171], v[176:179], v[40:43]
	v_mfma_f32_16x16x32_bf16 v[40:43], v[172:175], v[180:183], v[40:43]
	v_mfma_f32_16x16x32_bf16 v[24:27], v[168:171], v[184:187], v[24:27]
	v_mfma_f32_16x16x32_bf16 v[24:27], v[172:175], v[188:191], v[24:27]
	v_mfma_f32_16x16x32_bf16 v[8:11], v[168:171], v[192:195], v[8:11]
	v_mfma_f32_16x16x32_bf16 v[8:11], v[172:175], v[196:199], v[8:11]
	v_mfma_f32_16x16x32_bf16 v[0:3], v[168:171], v[200:203], v[0:3]
	v_mfma_f32_16x16x32_bf16 v[0:3], v[172:175], v[204:207], v[0:3]
	s_barrier
	s_add_i32 s93, s93, 2
	s_add_u32 s7, s7, 0x100
	s_addc_u32 s9, s9, 0
	s_cmp_gt_u32 s93, 5
	s_mov_b64 s[16:17], s[18:19]
	s_cbranch_scc0 .LBB0_1009
	s_branch .Lzexit_3

.LBB0_1325:
	s_add_u32 s74, s16, 0x100
	v_mov_b32_e32 v0, 0
	s_addc_u32 s94, s17, 0
	s_mov_b32 s95, -2
	s_add_u32 s16, s14, 0x100
	s_addc_u32 s17, s15, 0
	s_add_i32 s2, 0, 0x10000
	s_cmp_eq_u32 s95, 8
	s_cselect_b32 s23, s11, s17
	s_cselect_b32 s22, s10, s16
	v_add_u32_e32 v140, s2, v143
	s_cselect_b32 s19, s13, s94
	s_cselect_b32 s18, s12, s74
	s_add_i32 s58, 0, 0x14000
	ds_read_b128 v[146:149], v140
	ds_read_b128 v[150:153], v140 offset:1024
	ds_read_b128 v[154:157], v140 offset:2048
	ds_read_b128 v[158:161], v140 offset:3072
	v_add_u32_e32 v140, s58, v143
	ds_read_b128 v[162:165], v140
	ds_read_b128 v[166:169], v140 offset:1024
	ds_read_b128 v[170:173], v140 offset:2048
	ds_read_b128 v[174:177], v140 offset:3072
	v_lshl_add_u64 v[140:141], s[14:15], 0, v[136:137]
	s_add_i32 m0, s76, 0xc000
	ds_read_b128 v[178:181], v145
	ds_read_b128 v[182:185], v145 offset:1024
	ds_read_b128 v[186:189], v145 offset:2048
	ds_read_b128 v[190:193], v145 offset:3072
	ds_read_b128 v[194:197], v145 offset:4096
	ds_read_b128 v[198:201], v145 offset:5120
	ds_read_b128 v[202:205], v145 offset:6144
	ds_read_b128 v[206:209], v145 offset:7168
	global_load_lds_dwordx4 v[140:141], off
	v_lshl_add_u64 v[140:141], s[14:15], 0, v[138:139]
	s_add_i32 m0, s76, 0xe000
	s_nop 0
	global_load_lds_dwordx4 v[140:141], off
	s_waitcnt vmcnt(8)
	s_waitcnt lgkmcnt(0)
	s_barrier
	v_mfma_f32_16x16x32_bf16 v[124:127], v[146:149], v[178:181], 0
	v_mfma_f32_16x16x32_bf16 v[124:127], v[150:153], v[182:185], v[124:127]
	v_mfma_f32_16x16x32_bf16 v[108:111], v[146:149], v[186:189], 0
	v_mfma_f32_16x16x32_bf16 v[108:111], v[150:153], v[190:193], v[108:111]
	v_mfma_f32_16x16x32_bf16 v[92:95], v[146:149], v[194:197], 0
	v_mfma_f32_16x16x32_bf16 v[92:95], v[150:153], v[198:201], v[92:95]
	v_mfma_f32_16x16x32_bf16 v[76:79], v[146:149], v[202:205], 0
	v_mfma_f32_16x16x32_bf16 v[76:79], v[150:153], v[206:209], v[76:79]
	v_mfma_f32_16x16x32_bf16 v[120:123], v[154:157], v[178:181], 0
	v_mfma_f32_16x16x32_bf16 v[120:123], v[158:161], v[182:185], v[120:123]
	v_mfma_f32_16x16x32_bf16 v[104:107], v[154:157], v[186:189], 0
	v_mfma_f32_16x16x32_bf16 v[104:107], v[158:161], v[190:193], v[104:107]
	v_mfma_f32_16x16x32_bf16 v[88:91], v[154:157], v[194:197], 0
	v_mfma_f32_16x16x32_bf16 v[88:91], v[158:161], v[198:201], v[88:91]
	v_mfma_f32_16x16x32_bf16 v[72:75], v[154:157], v[202:205], 0
	v_mfma_f32_16x16x32_bf16 v[72:75], v[158:161], v[206:209], v[72:75]
	v_mfma_f32_16x16x32_bf16 v[116:119], v[162:165], v[178:181], 0
	v_mfma_f32_16x16x32_bf16 v[116:119], v[166:169], v[182:185], v[116:119]
	v_mfma_f32_16x16x32_bf16 v[100:103], v[162:165], v[186:189], 0
	v_mfma_f32_16x16x32_bf16 v[100:103], v[166:169], v[190:193], v[100:103]
	v_mfma_f32_16x16x32_bf16 v[84:87], v[162:165], v[194:197], 0
	v_mfma_f32_16x16x32_bf16 v[84:87], v[166:169], v[198:201], v[84:87]
	v_mfma_f32_16x16x32_bf16 v[68:71], v[162:165], v[202:205], 0
	v_mfma_f32_16x16x32_bf16 v[68:71], v[166:169], v[206:209], v[68:71]
	v_mfma_f32_16x16x32_bf16 v[112:115], v[170:173], v[178:181], 0
	v_mfma_f32_16x16x32_bf16 v[112:115], v[174:177], v[182:185], v[112:115]
	v_mfma_f32_16x16x32_bf16 v[96:99], v[170:173], v[186:189], 0
	v_mfma_f32_16x16x32_bf16 v[96:99], v[174:177], v[190:193], v[96:99]
	v_mfma_f32_16x16x32_bf16 v[80:83], v[170:173], v[194:197], 0
	v_mfma_f32_16x16x32_bf16 v[80:83], v[174:177], v[198:201], v[80:83]
	v_mfma_f32_16x16x32_bf16 v[64:67], v[170:173], v[202:205], 0
	v_mfma_f32_16x16x32_bf16 v[64:67], v[174:177], v[206:209], v[64:67]
	s_barrier
	s_add_i32 s2, s2, s50
	v_lshl_add_u64 v[140:141], s[18:19], 0, v[132:133]
	s_mov_b32 m0, s2
	ds_read_b128 v[178:181], v145 offset:16384
	ds_read_b128 v[182:185], v145 offset:17408
	ds_read_b128 v[186:189], v145 offset:18432
	ds_read_b128 v[190:193], v145 offset:19456
	ds_read_b128 v[194:197], v145 offset:20480
	ds_read_b128 v[198:201], v145 offset:21504
	ds_read_b128 v[202:205], v145 offset:22528
	ds_read_b128 v[206:209], v145 offset:23552
	global_load_lds_dwordx4 v[140:141], off
	s_add_i32 m0, s2, 0x2000
	s_add_u32 s2, s18, 0x30000
	v_lshl_add_u64 v[210:211], s[18:19], 0, v[128:129]
	s_addc_u32 s3, s19, 0
	s_add_i32 s14, s58, s50
	global_load_lds_dwordx4 v[210:211], off
	v_lshl_add_u64 v[212:213], s[2:3], 0, v[132:133]
	s_mov_b32 m0, s14
	v_lshl_add_u64 v[214:215], s[22:23], 0, v[130:131]
	global_load_lds_dwordx4 v[212:213], off
	v_lshl_add_u64 v[212:213], s[2:3], 0, v[128:129]
	s_add_i32 m0, s14, 0x2000
	s_nop 0
	global_load_lds_dwordx4 v[212:213], off
	v_lshl_add_u64 v[212:213], s[22:23], 0, v[134:135]
	s_mov_b32 m0, s76
	s_nop 0
	global_load_lds_dwordx4 v[212:213], off
	s_mov_b32 m0, s85
	s_nop 0
	global_load_lds_dwordx4 v[214:215], off
	s_waitcnt vmcnt(8)
	s_waitcnt lgkmcnt(0)
	s_barrier
	v_mfma_f32_16x16x32_bf16 v[60:63], v[146:149], v[178:181], 0
	v_mfma_f32_16x16x32_bf16 v[60:63], v[150:153], v[182:185], v[60:63]
	v_mfma_f32_16x16x32_bf16 v[44:47], v[146:149], v[186:189], 0
	v_mfma_f32_16x16x32_bf16 v[44:47], v[150:153], v[190:193], v[44:47]
	v_mfma_f32_16x16x32_bf16 v[28:31], v[146:149], v[194:197], 0
	v_mfma_f32_16x16x32_bf16 v[28:31], v[150:153], v[198:201], v[28:31]
	v_mfma_f32_16x16x32_bf16 v[12:15], v[146:149], v[202:205], 0
	v_mfma_f32_16x16x32_bf16 v[12:15], v[150:153], v[206:209], v[12:15]
	v_mfma_f32_16x16x32_bf16 v[56:59], v[154:157], v[178:181], 0
	v_mfma_f32_16x16x32_bf16 v[56:59], v[158:161], v[182:185], v[56:59]
	v_mfma_f32_16x16x32_bf16 v[40:43], v[154:157], v[186:189], 0
	v_mfma_f32_16x16x32_bf16 v[40:43], v[158:161], v[190:193], v[40:43]
	v_mfma_f32_16x16x32_bf16 v[24:27], v[154:157], v[194:197], 0
	v_mfma_f32_16x16x32_bf16 v[24:27], v[158:161], v[198:201], v[24:27]
	v_mfma_f32_16x16x32_bf16 v[8:11], v[154:157], v[202:205], 0
	v_mfma_f32_16x16x32_bf16 v[8:11], v[158:161], v[206:209], v[8:11]
	v_mfma_f32_16x16x32_bf16 v[52:55], v[162:165], v[178:181], 0
	v_mfma_f32_16x16x32_bf16 v[52:55], v[166:169], v[182:185], v[52:55]
	v_mfma_f32_16x16x32_bf16 v[36:39], v[162:165], v[186:189], 0
	v_mfma_f32_16x16x32_bf16 v[36:39], v[166:169], v[190:193], v[36:39]
	v_mfma_f32_16x16x32_bf16 v[20:23], v[162:165], v[194:197], 0
	v_mfma_f32_16x16x32_bf16 v[20:23], v[166:169], v[198:201], v[20:23]
	v_mfma_f32_16x16x32_bf16 v[4:7], v[162:165], v[202:205], 0
	v_mfma_f32_16x16x32_bf16 v[4:7], v[166:169], v[206:209], v[4:7]
	v_mfma_f32_16x16x32_bf16 v[48:51], v[170:173], v[178:181], 0
	v_mfma_f32_16x16x32_bf16 v[48:51], v[174:177], v[182:185], v[48:51]
	v_mfma_f32_16x16x32_bf16 v[32:35], v[170:173], v[186:189], 0
	v_mfma_f32_16x16x32_bf16 v[32:35], v[174:177], v[190:193], v[32:35]
	v_mfma_f32_16x16x32_bf16 v[16:19], v[170:173], v[194:197], 0
	v_mfma_f32_16x16x32_bf16 v[16:19], v[174:177], v[198:201], v[16:19]
	v_mfma_f32_16x16x32_bf16 v[0:3], v[170:173], v[202:205], 0
	v_mfma_f32_16x16x32_bf16 v[0:3], v[174:177], v[206:209], v[0:3]
	s_barrier
	s_add_i32 s14, 0, 0x18000
	s_add_i32 s15, 0, 0x1c000
	v_add_u32_e32 v158, s14, v143
	v_add_u32_e32 v174, s15, v143
	ds_read_b128 v[146:149], v158
	ds_read_b128 v[150:153], v158 offset:1024
	ds_read_b128 v[154:157], v158 offset:2048
	ds_read_b128 v[158:161], v158 offset:3072
	ds_read_b128 v[162:165], v174
	ds_read_b128 v[166:169], v174 offset:1024
	ds_read_b128 v[170:173], v174 offset:2048
	ds_read_b128 v[174:177], v174 offset:3072
	s_add_u32 s2, s22, 0x30000
	s_addc_u32 s3, s23, 0
	s_mov_b32 m0, s86
	v_lshl_add_u64 v[218:219], s[2:3], 0, v[134:135]
	ds_read_b128 v[178:181], v145 offset:32768
	ds_read_b128 v[182:185], v145 offset:33792
	ds_read_b128 v[186:189], v145 offset:34816
	ds_read_b128 v[190:193], v145 offset:35840
	ds_read_b128 v[194:197], v145 offset:36864
	ds_read_b128 v[198:201], v145 offset:37888
	ds_read_b128 v[202:205], v145 offset:38912
	ds_read_b128 v[206:209], v145 offset:39936
	global_load_lds_dwordx4 v[218:219], off
	v_lshl_add_u64 v[218:219], s[2:3], 0, v[130:131]
	s_mov_b32 m0, s87
	s_nop 0
	global_load_lds_dwordx4 v[218:219], off
	s_waitcnt vmcnt(8)
	s_waitcnt lgkmcnt(0)
	s_barrier
	v_mfma_f32_16x16x32_bf16 v[124:127], v[146:149], v[178:181], v[124:127]
	v_mfma_f32_16x16x32_bf16 v[124:127], v[150:153], v[182:185], v[124:127]
	v_mfma_f32_16x16x32_bf16 v[108:111], v[146:149], v[186:189], v[108:111]
	v_mfma_f32_16x16x32_bf16 v[108:111], v[150:153], v[190:193], v[108:111]
	v_mfma_f32_16x16x32_bf16 v[92:95], v[146:149], v[194:197], v[92:95]
	v_mfma_f32_16x16x32_bf16 v[92:95], v[150:153], v[198:201], v[92:95]
	v_mfma_f32_16x16x32_bf16 v[76:79], v[146:149], v[202:205], v[76:79]
	v_mfma_f32_16x16x32_bf16 v[76:79], v[150:153], v[206:209], v[76:79]
	v_mfma_f32_16x16x32_bf16 v[120:123], v[154:157], v[178:181], v[120:123]
	v_mfma_f32_16x16x32_bf16 v[120:123], v[158:161], v[182:185], v[120:123]
	v_mfma_f32_16x16x32_bf16 v[104:107], v[154:157], v[186:189], v[104:107]
	v_mfma_f32_16x16x32_bf16 v[104:107], v[158:161], v[190:193], v[104:107]
	v_mfma_f32_16x16x32_bf16 v[88:91], v[154:157], v[194:197], v[88:91]
	v_mfma_f32_16x16x32_bf16 v[88:91], v[158:161], v[198:201], v[88:91]
	v_mfma_f32_16x16x32_bf16 v[72:75], v[154:157], v[202:205], v[72:75]
	v_mfma_f32_16x16x32_bf16 v[72:75], v[158:161], v[206:209], v[72:75]
	v_mfma_f32_16x16x32_bf16 v[116:119], v[162:165], v[178:181], v[116:119]
	v_mfma_f32_16x16x32_bf16 v[116:119], v[166:169], v[182:185], v[116:119]
	v_mfma_f32_16x16x32_bf16 v[100:103], v[162:165], v[186:189], v[100:103]
	v_mfma_f32_16x16x32_bf16 v[100:103], v[166:169], v[190:193], v[100:103]
	v_mfma_f32_16x16x32_bf16 v[84:87], v[162:165], v[194:197], v[84:87]
	v_mfma_f32_16x16x32_bf16 v[84:87], v[166:169], v[198:201], v[84:87]
	v_mfma_f32_16x16x32_bf16 v[68:71], v[162:165], v[202:205], v[68:71]
	v_mfma_f32_16x16x32_bf16 v[68:71], v[166:169], v[206:209], v[68:71]
	v_mfma_f32_16x16x32_bf16 v[112:115], v[170:173], v[178:181], v[112:115]
	v_mfma_f32_16x16x32_bf16 v[112:115], v[174:177], v[182:185], v[112:115]
	v_mfma_f32_16x16x32_bf16 v[96:99], v[170:173], v[186:189], v[96:99]
	v_mfma_f32_16x16x32_bf16 v[96:99], v[174:177], v[190:193], v[96:99]
	v_mfma_f32_16x16x32_bf16 v[80:83], v[170:173], v[194:197], v[80:83]
	v_mfma_f32_16x16x32_bf16 v[80:83], v[174:177], v[198:201], v[80:83]
	v_mfma_f32_16x16x32_bf16 v[64:67], v[170:173], v[202:205], v[64:67]
	v_mfma_f32_16x16x32_bf16 v[64:67], v[174:177], v[206:209], v[64:67]
	s_barrier
	s_add_i32 s2, s14, s50
	v_lshl_add_u64 v[140:141], v[140:141], 0, s[60:61]
	s_mov_b32 m0, s2
	ds_read_b128 v[178:181], v145 offset:49152
	ds_read_b128 v[182:185], v145 offset:50176
	ds_read_b128 v[186:189], v145 offset:51200
	ds_read_b128 v[190:193], v145 offset:52224
	ds_read_b128 v[194:197], v145 offset:53248
	ds_read_b128 v[198:201], v145 offset:54272
	ds_read_b128 v[202:205], v145 offset:55296
	ds_read_b128 v[206:209], v145 offset:56320
	global_load_lds_dwordx4 v[140:141], off
	s_add_i32 m0, s2, 0x2000
	s_add_u32 s2, s18, 0x30080
	v_lshl_add_u64 v[140:141], v[210:211], 0, s[60:61]
	s_addc_u32 s3, s19, 0
	s_add_i32 s14, s15, s50
	global_load_lds_dwordx4 v[140:141], off
	v_lshl_add_u64 v[140:141], s[2:3], 0, v[132:133]
	s_mov_b32 m0, s14
	s_nop 0
	global_load_lds_dwordx4 v[140:141], off
	v_lshl_add_u64 v[140:141], s[2:3], 0, v[128:129]
	s_add_i32 m0, s14, 0x2000
	s_nop 0
	global_load_lds_dwordx4 v[140:141], off
	v_lshl_add_u64 v[140:141], v[212:213], 0, s[60:61]
	s_mov_b32 m0, s88
	s_nop 0
	global_load_lds_dwordx4 v[140:141], off
	v_lshl_add_u64 v[140:141], v[214:215], 0, s[60:61]
	s_mov_b32 m0, s89
	s_nop 0
	global_load_lds_dwordx4 v[140:141], off
	s_waitcnt vmcnt(8)
	s_waitcnt lgkmcnt(0)
	s_barrier
	v_mfma_f32_16x16x32_bf16 v[60:63], v[146:149], v[178:181], v[60:63]
	v_mfma_f32_16x16x32_bf16 v[60:63], v[150:153], v[182:185], v[60:63]
	v_mfma_f32_16x16x32_bf16 v[44:47], v[146:149], v[186:189], v[44:47]
	v_mfma_f32_16x16x32_bf16 v[44:47], v[150:153], v[190:193], v[44:47]
	v_mfma_f32_16x16x32_bf16 v[28:31], v[146:149], v[194:197], v[28:31]
	v_mfma_f32_16x16x32_bf16 v[28:31], v[150:153], v[198:201], v[28:31]
	v_mfma_f32_16x16x32_bf16 v[12:15], v[146:149], v[202:205], v[12:15]
	v_mfma_f32_16x16x32_bf16 v[12:15], v[150:153], v[206:209], v[12:15]
	v_mfma_f32_16x16x32_bf16 v[56:59], v[154:157], v[178:181], v[56:59]
	v_mfma_f32_16x16x32_bf16 v[56:59], v[158:161], v[182:185], v[56:59]
	v_mfma_f32_16x16x32_bf16 v[40:43], v[154:157], v[186:189], v[40:43]
	v_mfma_f32_16x16x32_bf16 v[40:43], v[158:161], v[190:193], v[40:43]
	v_mfma_f32_16x16x32_bf16 v[24:27], v[154:157], v[194:197], v[24:27]
	v_mfma_f32_16x16x32_bf16 v[24:27], v[158:161], v[198:201], v[24:27]
	v_mfma_f32_16x16x32_bf16 v[8:11], v[154:157], v[202:205], v[8:11]
	v_mfma_f32_16x16x32_bf16 v[8:11], v[158:161], v[206:209], v[8:11]
	v_mfma_f32_16x16x32_bf16 v[52:55], v[162:165], v[178:181], v[52:55]
	v_mfma_f32_16x16x32_bf16 v[52:55], v[166:169], v[182:185], v[52:55]
	v_mfma_f32_16x16x32_bf16 v[36:39], v[162:165], v[186:189], v[36:39]
	v_mfma_f32_16x16x32_bf16 v[36:39], v[166:169], v[190:193], v[36:39]
	v_mfma_f32_16x16x32_bf16 v[20:23], v[162:165], v[194:197], v[20:23]
	v_mfma_f32_16x16x32_bf16 v[20:23], v[166:169], v[198:201], v[20:23]
	v_mfma_f32_16x16x32_bf16 v[4:7], v[162:165], v[202:205], v[4:7]
	v_mfma_f32_16x16x32_bf16 v[4:7], v[166:169], v[206:209], v[4:7]
	v_mfma_f32_16x16x32_bf16 v[48:51], v[170:173], v[178:181], v[48:51]
	v_mfma_f32_16x16x32_bf16 v[48:51], v[174:177], v[182:185], v[48:51]
	v_mfma_f32_16x16x32_bf16 v[32:35], v[170:173], v[186:189], v[32:35]
	v_mfma_f32_16x16x32_bf16 v[32:35], v[174:177], v[190:193], v[32:35]
	v_mfma_f32_16x16x32_bf16 v[16:19], v[170:173], v[194:197], v[16:19]
	v_mfma_f32_16x16x32_bf16 v[16:19], v[174:177], v[198:201], v[16:19]
	v_mfma_f32_16x16x32_bf16 v[0:3], v[170:173], v[202:205], v[0:3]
	v_mfma_f32_16x16x32_bf16 v[0:3], v[174:177], v[206:209], v[0:3]
	s_barrier
	s_add_i32 s95, s95, 2
	s_add_u32 s74, s74, 0x100
	s_addc_u32 s94, s94, 0
	s_cmp_gt_u32 s95, 9
	s_mov_b64 s[14:15], s[16:17]
	s_cbranch_scc0 .LBB0_1326
	s_branch .Lzexit_4

.LBB0_1663:
	s_ashr_i32 s17, s16, 31
	s_lshl_b64 s[18:19], s[16:17], 20
	s_add_u32 s18, s27, s18
	s_addc_u32 s19, s31, s19
	s_and_b64 s[22:23], s[4:5], exec
	s_cselect_b32 s17, s19, s53
	s_cselect_b32 s96, s18, s52
	s_ashr_i32 s15, s14, 31
	s_lshl_b64 s[22:23], s[14:15], 20
	s_add_u32 s22, s36, s22
	s_addc_u32 s23, s41, s23
	s_and_b64 s[54:55], s[4:5], exec
	s_cselect_b32 s15, s23, s93
	s_cselect_b32 s97, s22, s92
	s_add_u32 s90, s52, 0x80080
	s_addc_u32 s91, s53, 0
	s_add_u32 s92, s92, 0x100
	v_mov_b32_e32 v0, 0
	s_addc_u32 s93, s93, 0
	s_mov_b32 vcc_lo, -2
	s_add_u32 s52, s90, 0xfff80080
	s_addc_u32 s53, s91, -1
	s_add_i32 s58, 0, 0x10000
	s_cmp_eq_u32 vcc_lo, 28
	s_cselect_b32 s55, s17, s53
	s_cselect_b32 s54, s96, s52
	s_cselect_b32 s53, s15, s93
	s_cselect_b32 s52, s97, s92
	s_add_i32 s81, 0, 0x14000
	v_add_u32_e32 v140, s58, v163
	v_add_u32_e32 v170, s81, v163
	ds_read_b128 v[128:131], v140
	ds_read_b128 v[132:135], v140 offset:1024
	ds_read_b128 v[136:139], v140 offset:2048
	ds_read_b128 v[140:143], v140 offset:3072
	ds_read_b128 v[154:157], v170
	ds_read_b128 v[158:161], v170 offset:1024
	ds_read_b128 v[166:169], v170 offset:2048
	ds_read_b128 v[174:177], v170 offset:3072
	v_lshl_add_u64 v[170:171], s[90:91], 0, v[150:151]
	s_add_i32 m0, s76, 0xc000
	ds_read_b128 v[178:181], v165
	ds_read_b128 v[182:185], v165 offset:1024
	ds_read_b128 v[186:189], v165 offset:2048
	ds_read_b128 v[190:193], v165 offset:3072
	ds_read_b128 v[194:197], v165 offset:4096
	ds_read_b128 v[198:201], v165 offset:5120
	ds_read_b128 v[202:205], v165 offset:6144
	ds_read_b128 v[206:209], v165 offset:7168
	global_load_lds_dwordx4 v[170:171], off
	v_lshl_add_u64 v[170:171], s[90:91], 0, v[152:153]
	s_add_i32 m0, s76, 0xe000
	s_nop 0
	global_load_lds_dwordx4 v[170:171], off
	s_waitcnt vmcnt(8)
	s_waitcnt lgkmcnt(0)
	s_barrier
	v_mfma_f32_16x16x32_bf16 v[124:127], v[128:131], v[178:181], 0
	v_mfma_f32_16x16x32_bf16 v[124:127], v[132:135], v[182:185], v[124:127]
	v_mfma_f32_16x16x32_bf16 v[116:119], v[128:131], v[186:189], 0
	v_mfma_f32_16x16x32_bf16 v[116:119], v[132:135], v[190:193], v[116:119]
	v_mfma_f32_16x16x32_bf16 v[96:99], v[128:131], v[194:197], 0
	v_mfma_f32_16x16x32_bf16 v[96:99], v[132:135], v[198:201], v[96:99]
	v_mfma_f32_16x16x32_bf16 v[80:83], v[128:131], v[202:205], 0
	v_mfma_f32_16x16x32_bf16 v[80:83], v[132:135], v[206:209], v[80:83]
	v_mfma_f32_16x16x32_bf16 v[120:123], v[136:139], v[178:181], 0
	v_mfma_f32_16x16x32_bf16 v[120:123], v[140:143], v[182:185], v[120:123]
	v_mfma_f32_16x16x32_bf16 v[112:115], v[136:139], v[186:189], 0
	v_mfma_f32_16x16x32_bf16 v[112:115], v[140:143], v[190:193], v[112:115]
	v_mfma_f32_16x16x32_bf16 v[88:91], v[136:139], v[194:197], 0
	v_mfma_f32_16x16x32_bf16 v[88:91], v[140:143], v[198:201], v[88:91]
	v_mfma_f32_16x16x32_bf16 v[72:75], v[136:139], v[202:205], 0
	v_mfma_f32_16x16x32_bf16 v[72:75], v[140:143], v[206:209], v[72:75]
	v_mfma_f32_16x16x32_bf16 v[108:111], v[154:157], v[178:181], 0
	v_mfma_f32_16x16x32_bf16 v[108:111], v[158:161], v[182:185], v[108:111]
	v_mfma_f32_16x16x32_bf16 v[100:103], v[154:157], v[186:189], 0
	v_mfma_f32_16x16x32_bf16 v[100:103], v[158:161], v[190:193], v[100:103]
	v_mfma_f32_16x16x32_bf16 v[84:87], v[154:157], v[194:197], 0
	v_mfma_f32_16x16x32_bf16 v[84:87], v[158:161], v[198:201], v[84:87]
	v_mfma_f32_16x16x32_bf16 v[68:71], v[154:157], v[202:205], 0
	v_mfma_f32_16x16x32_bf16 v[68:71], v[158:161], v[206:209], v[68:71]
	v_mfma_f32_16x16x32_bf16 v[104:107], v[166:169], v[178:181], 0
	v_mfma_f32_16x16x32_bf16 v[104:107], v[174:177], v[182:185], v[104:107]
	v_mfma_f32_16x16x32_bf16 v[92:95], v[166:169], v[186:189], 0
	v_mfma_f32_16x16x32_bf16 v[92:95], v[174:177], v[190:193], v[92:95]
	v_mfma_f32_16x16x32_bf16 v[76:79], v[166:169], v[194:197], 0
	v_mfma_f32_16x16x32_bf16 v[76:79], v[174:177], v[198:201], v[76:79]
	v_mfma_f32_16x16x32_bf16 v[64:67], v[166:169], v[202:205], 0
	v_mfma_f32_16x16x32_bf16 v[64:67], v[174:177], v[206:209], v[64:67]
	s_barrier
	s_add_i32 s58, s58, s50
	v_lshl_add_u64 v[170:171], s[52:53], 0, v[216:217]
	s_mov_b32 m0, s58
	ds_read_b128 v[178:181], v165 offset:16384
	ds_read_b128 v[182:185], v165 offset:17408
	ds_read_b128 v[186:189], v165 offset:18432
	ds_read_b128 v[190:193], v165 offset:19456
	ds_read_b128 v[194:197], v165 offset:20480
	ds_read_b128 v[198:201], v165 offset:21504
	ds_read_b128 v[202:205], v165 offset:22528
	ds_read_b128 v[206:209], v165 offset:23552
	global_load_lds_dwordx4 v[170:171], off
	s_add_i32 m0, s58, 0x2000
	s_add_u32 s58, s52, 0x80000
	v_lshl_add_u64 v[210:211], s[52:53], 0, v[148:149]
	s_addc_u32 s59, s53, 0
	s_add_i32 s81, s81, s50
	global_load_lds_dwordx4 v[210:211], off
	v_lshl_add_u64 v[212:213], s[58:59], 0, v[216:217]
	s_mov_b32 m0, s81
	v_lshl_add_u64 v[214:215], s[54:55], 0, v[146:147]
	global_load_lds_dwordx4 v[212:213], off
	v_lshl_add_u64 v[212:213], s[58:59], 0, v[148:149]
	s_add_i32 m0, s81, 0x2000
	s_nop 0
	global_load_lds_dwordx4 v[212:213], off
	v_lshl_add_u64 v[212:213], s[54:55], 0, v[144:145]
	s_mov_b32 m0, s76
	s_nop 0
	global_load_lds_dwordx4 v[212:213], off
	s_mov_b32 m0, s45
	s_nop 0
	global_load_lds_dwordx4 v[214:215], off
	s_waitcnt vmcnt(8)
	s_waitcnt lgkmcnt(0)
	s_barrier
	v_mfma_f32_16x16x32_bf16 v[60:63], v[128:131], v[178:181], 0
	v_mfma_f32_16x16x32_bf16 v[60:63], v[132:135], v[182:185], v[60:63]
	v_mfma_f32_16x16x32_bf16 v[48:51], v[128:131], v[186:189], 0
	v_mfma_f32_16x16x32_bf16 v[48:51], v[132:135], v[190:193], v[48:51]
	v_mfma_f32_16x16x32_bf16 v[32:35], v[128:131], v[194:197], 0
	v_mfma_f32_16x16x32_bf16 v[32:35], v[132:135], v[198:201], v[32:35]
	v_mfma_f32_16x16x32_bf16 v[16:19], v[128:131], v[202:205], 0
	v_mfma_f32_16x16x32_bf16 v[16:19], v[132:135], v[206:209], v[16:19]
	v_mfma_f32_16x16x32_bf16 v[56:59], v[136:139], v[178:181], 0
	v_mfma_f32_16x16x32_bf16 v[56:59], v[140:143], v[182:185], v[56:59]
	v_mfma_f32_16x16x32_bf16 v[40:43], v[136:139], v[186:189], 0
	v_mfma_f32_16x16x32_bf16 v[40:43], v[140:143], v[190:193], v[40:43]
	v_mfma_f32_16x16x32_bf16 v[24:27], v[136:139], v[194:197], 0
	v_mfma_f32_16x16x32_bf16 v[24:27], v[140:143], v[198:201], v[24:27]
	v_mfma_f32_16x16x32_bf16 v[8:11], v[136:139], v[202:205], 0
	v_mfma_f32_16x16x32_bf16 v[8:11], v[140:143], v[206:209], v[8:11]
	v_mfma_f32_16x16x32_bf16 v[52:55], v[154:157], v[178:181], 0
	v_mfma_f32_16x16x32_bf16 v[52:55], v[158:161], v[182:185], v[52:55]
	v_mfma_f32_16x16x32_bf16 v[36:39], v[154:157], v[186:189], 0
	v_mfma_f32_16x16x32_bf16 v[36:39], v[158:161], v[190:193], v[36:39]
	v_mfma_f32_16x16x32_bf16 v[20:23], v[154:157], v[194:197], 0
	v_mfma_f32_16x16x32_bf16 v[20:23], v[158:161], v[198:201], v[20:23]
	v_mfma_f32_16x16x32_bf16 v[4:7], v[154:157], v[202:205], 0
	v_mfma_f32_16x16x32_bf16 v[4:7], v[158:161], v[206:209], v[4:7]
	v_mfma_f32_16x16x32_bf16 v[44:47], v[166:169], v[178:181], 0
	v_mfma_f32_16x16x32_bf16 v[44:47], v[174:177], v[182:185], v[44:47]
	v_mfma_f32_16x16x32_bf16 v[28:31], v[166:169], v[186:189], 0
	v_mfma_f32_16x16x32_bf16 v[28:31], v[174:177], v[190:193], v[28:31]
	v_mfma_f32_16x16x32_bf16 v[12:15], v[166:169], v[194:197], 0
	v_mfma_f32_16x16x32_bf16 v[12:15], v[174:177], v[198:201], v[12:15]
	v_mfma_f32_16x16x32_bf16 v[0:3], v[166:169], v[202:205], 0
	v_mfma_f32_16x16x32_bf16 v[0:3], v[174:177], v[206:209], v[0:3]
	s_barrier
	s_add_i32 s58, 0, 0x18000
	s_add_i32 s59, 0, 0x1c000
	v_add_u32_e32 v140, s58, v163
	v_add_u32_e32 v173, s59, v163
	ds_read_b128 v[128:131], v140
	ds_read_b128 v[132:135], v140 offset:1024
	ds_read_b128 v[136:139], v140 offset:2048
	ds_read_b128 v[140:143], v140 offset:3072
	ds_read_b128 v[154:157], v173
	ds_read_b128 v[158:161], v173 offset:1024
	ds_read_b128 v[166:169], v173 offset:2048
	ds_read_b128 v[174:177], v173 offset:3072
	s_add_u32 s54, s54, 0x80000
	s_addc_u32 s55, s55, 0
	s_mov_b32 m0, s65
	v_lshl_add_u64 v[218:219], s[54:55], 0, v[144:145]
	ds_read_b128 v[178:181], v165 offset:32768
	ds_read_b128 v[182:185], v165 offset:33792
	ds_read_b128 v[186:189], v165 offset:34816
	ds_read_b128 v[190:193], v165 offset:35840
	ds_read_b128 v[194:197], v165 offset:36864
	ds_read_b128 v[198:201], v165 offset:37888
	ds_read_b128 v[202:205], v165 offset:38912
	ds_read_b128 v[206:209], v165 offset:39936
	global_load_lds_dwordx4 v[218:219], off
	v_lshl_add_u64 v[218:219], s[54:55], 0, v[146:147]
	s_mov_b32 m0, s72
	s_nop 0
	global_load_lds_dwordx4 v[218:219], off
	s_waitcnt vmcnt(8)
	s_waitcnt lgkmcnt(0)
	s_barrier
	v_mfma_f32_16x16x32_bf16 v[124:127], v[128:131], v[178:181], v[124:127]
	v_mfma_f32_16x16x32_bf16 v[124:127], v[132:135], v[182:185], v[124:127]
	v_mfma_f32_16x16x32_bf16 v[116:119], v[128:131], v[186:189], v[116:119]
	v_mfma_f32_16x16x32_bf16 v[116:119], v[132:135], v[190:193], v[116:119]
	v_mfma_f32_16x16x32_bf16 v[96:99], v[128:131], v[194:197], v[96:99]
	v_mfma_f32_16x16x32_bf16 v[96:99], v[132:135], v[198:201], v[96:99]
	v_mfma_f32_16x16x32_bf16 v[80:83], v[128:131], v[202:205], v[80:83]
	v_mfma_f32_16x16x32_bf16 v[80:83], v[132:135], v[206:209], v[80:83]
	v_mfma_f32_16x16x32_bf16 v[120:123], v[136:139], v[178:181], v[120:123]
	v_mfma_f32_16x16x32_bf16 v[120:123], v[140:143], v[182:185], v[120:123]
	v_mfma_f32_16x16x32_bf16 v[112:115], v[136:139], v[186:189], v[112:115]
	v_mfma_f32_16x16x32_bf16 v[112:115], v[140:143], v[190:193], v[112:115]
	v_mfma_f32_16x16x32_bf16 v[88:91], v[136:139], v[194:197], v[88:91]
	v_mfma_f32_16x16x32_bf16 v[88:91], v[140:143], v[198:201], v[88:91]
	v_mfma_f32_16x16x32_bf16 v[72:75], v[136:139], v[202:205], v[72:75]
	v_mfma_f32_16x16x32_bf16 v[72:75], v[140:143], v[206:209], v[72:75]
	v_mfma_f32_16x16x32_bf16 v[108:111], v[154:157], v[178:181], v[108:111]
	v_mfma_f32_16x16x32_bf16 v[108:111], v[158:161], v[182:185], v[108:111]
	v_mfma_f32_16x16x32_bf16 v[100:103], v[154:157], v[186:189], v[100:103]
	v_mfma_f32_16x16x32_bf16 v[100:103], v[158:161], v[190:193], v[100:103]
	v_mfma_f32_16x16x32_bf16 v[84:87], v[154:157], v[194:197], v[84:87]
	v_mfma_f32_16x16x32_bf16 v[84:87], v[158:161], v[198:201], v[84:87]
	v_mfma_f32_16x16x32_bf16 v[68:71], v[154:157], v[202:205], v[68:71]
	v_mfma_f32_16x16x32_bf16 v[68:71], v[158:161], v[206:209], v[68:71]
	v_mfma_f32_16x16x32_bf16 v[104:107], v[166:169], v[178:181], v[104:107]
	v_mfma_f32_16x16x32_bf16 v[104:107], v[174:177], v[182:185], v[104:107]
	v_mfma_f32_16x16x32_bf16 v[92:95], v[166:169], v[186:189], v[92:95]
	v_mfma_f32_16x16x32_bf16 v[92:95], v[174:177], v[190:193], v[92:95]
	v_mfma_f32_16x16x32_bf16 v[76:79], v[166:169], v[194:197], v[76:79]
	v_mfma_f32_16x16x32_bf16 v[76:79], v[174:177], v[198:201], v[76:79]
	v_mfma_f32_16x16x32_bf16 v[64:67], v[166:169], v[202:205], v[64:67]
	v_mfma_f32_16x16x32_bf16 v[64:67], v[174:177], v[206:209], v[64:67]
	s_barrier
	s_add_i32 s54, s58, s50
	v_lshl_add_u64 v[170:171], v[170:171], 0, s[60:61]
	s_mov_b32 m0, s54
	ds_read_b128 v[178:181], v165 offset:49152
	ds_read_b128 v[182:185], v165 offset:50176
	ds_read_b128 v[186:189], v165 offset:51200
	ds_read_b128 v[190:193], v165 offset:52224
	ds_read_b128 v[194:197], v165 offset:53248
	ds_read_b128 v[198:201], v165 offset:54272
	ds_read_b128 v[202:205], v165 offset:55296
	ds_read_b128 v[206:209], v165 offset:56320
	global_load_lds_dwordx4 v[170:171], off
	s_add_i32 m0, s54, 0x2000
	s_add_u32 s52, s52, 0x80080
	v_lshl_add_u64 v[170:171], v[210:211], 0, s[60:61]
	s_addc_u32 s53, s53, 0
	s_add_i32 s54, s59, s50
	global_load_lds_dwordx4 v[170:171], off
	v_lshl_add_u64 v[170:171], s[52:53], 0, v[216:217]
	s_mov_b32 m0, s54
	s_nop 0
	global_load_lds_dwordx4 v[170:171], off
	v_lshl_add_u64 v[170:171], s[52:53], 0, v[148:149]
	s_add_i32 m0, s54, 0x2000
	s_nop 0
	global_load_lds_dwordx4 v[170:171], off
	v_lshl_add_u64 v[170:171], v[212:213], 0, s[60:61]
	s_mov_b32 m0, s87
	s_nop 0
	global_load_lds_dwordx4 v[170:171], off
	v_lshl_add_u64 v[170:171], v[214:215], 0, s[60:61]
	s_mov_b32 m0, s89
	s_nop 0
	global_load_lds_dwordx4 v[170:171], off
	s_waitcnt vmcnt(8)
	s_waitcnt lgkmcnt(0)
	s_barrier
	v_mfma_f32_16x16x32_bf16 v[60:63], v[128:131], v[178:181], v[60:63]
	v_mfma_f32_16x16x32_bf16 v[60:63], v[132:135], v[182:185], v[60:63]
	v_mfma_f32_16x16x32_bf16 v[48:51], v[128:131], v[186:189], v[48:51]
	v_mfma_f32_16x16x32_bf16 v[48:51], v[132:135], v[190:193], v[48:51]
	v_mfma_f32_16x16x32_bf16 v[32:35], v[128:131], v[194:197], v[32:35]
	v_mfma_f32_16x16x32_bf16 v[32:35], v[132:135], v[198:201], v[32:35]
	v_mfma_f32_16x16x32_bf16 v[16:19], v[128:131], v[202:205], v[16:19]
	v_mfma_f32_16x16x32_bf16 v[16:19], v[132:135], v[206:209], v[16:19]
	v_mfma_f32_16x16x32_bf16 v[56:59], v[136:139], v[178:181], v[56:59]
	v_mfma_f32_16x16x32_bf16 v[56:59], v[140:143], v[182:185], v[56:59]
	v_mfma_f32_16x16x32_bf16 v[40:43], v[136:139], v[186:189], v[40:43]
	v_mfma_f32_16x16x32_bf16 v[40:43], v[140:143], v[190:193], v[40:43]
	v_mfma_f32_16x16x32_bf16 v[24:27], v[136:139], v[194:197], v[24:27]
	v_mfma_f32_16x16x32_bf16 v[24:27], v[140:143], v[198:201], v[24:27]
	v_mfma_f32_16x16x32_bf16 v[8:11], v[136:139], v[202:205], v[8:11]
	v_mfma_f32_16x16x32_bf16 v[8:11], v[140:143], v[206:209], v[8:11]
	v_mfma_f32_16x16x32_bf16 v[52:55], v[154:157], v[178:181], v[52:55]
	v_mfma_f32_16x16x32_bf16 v[52:55], v[158:161], v[182:185], v[52:55]
	v_mfma_f32_16x16x32_bf16 v[36:39], v[154:157], v[186:189], v[36:39]
	v_mfma_f32_16x16x32_bf16 v[36:39], v[158:161], v[190:193], v[36:39]
	v_mfma_f32_16x16x32_bf16 v[20:23], v[154:157], v[194:197], v[20:23]
	v_mfma_f32_16x16x32_bf16 v[20:23], v[158:161], v[198:201], v[20:23]
	v_mfma_f32_16x16x32_bf16 v[4:7], v[154:157], v[202:205], v[4:7]
	v_mfma_f32_16x16x32_bf16 v[4:7], v[158:161], v[206:209], v[4:7]
	v_mfma_f32_16x16x32_bf16 v[44:47], v[166:169], v[178:181], v[44:47]
	v_mfma_f32_16x16x32_bf16 v[44:47], v[174:177], v[182:185], v[44:47]
	v_mfma_f32_16x16x32_bf16 v[28:31], v[166:169], v[186:189], v[28:31]
	v_mfma_f32_16x16x32_bf16 v[28:31], v[174:177], v[190:193], v[28:31]
	v_mfma_f32_16x16x32_bf16 v[12:15], v[166:169], v[194:197], v[12:15]
	v_mfma_f32_16x16x32_bf16 v[12:15], v[174:177], v[198:201], v[12:15]
	v_mfma_f32_16x16x32_bf16 v[0:3], v[166:169], v[202:205], v[0:3]
	v_mfma_f32_16x16x32_bf16 v[0:3], v[174:177], v[206:209], v[0:3]
	s_barrier
	s_add_i32 vcc_lo, vcc_lo, 2
	s_add_u32 s90, s90, 0x100
	s_addc_u32 s91, s91, 0
	s_add_u32 s92, s92, 0x100
	s_addc_u32 s93, s93, 0
	s_cmp_gt_u32 vcc_lo, 29
	s_cbranch_scc0 .LBB0_1664
	s_branch .Lzexit_5

.LBB0_1930:
	s_ashr_i32 s13, s12, 31
	s_lshl_b64 s[14:15], s[12:13], 20
	s_add_u32 s14, s41, s14
	s_addc_u32 s15, s42, s15
	s_and_b64 s[16:17], s[4:5], exec
	s_cselect_b32 s13, s15, s23
	s_cselect_b32 s91, s14, s22
	s_ashr_i32 s11, s10, 31
	s_lshl_b64 s[16:17], s[10:11], 20
	s_add_u32 s16, s45, s16
	s_addc_u32 s17, s65, s17
	s_and_b64 s[54:55], s[4:5], exec
	s_cselect_b32 s11, s17, s53
	s_cselect_b32 s92, s16, s52
	s_add_u32 s22, s22, 0x80080
	s_addc_u32 s23, s23, 0
	s_add_u32 s93, s52, 0x100
	v_mov_b32_e32 v4, 0
	s_addc_u32 s94, s53, 0
	s_mov_b32 s95, -2
	s_add_u32 s52, s22, 0xfff80080
	s_addc_u32 s53, s23, -1
	s_add_i32 s58, 0, 0x10000
	s_cmp_eq_u32 s95, 28
	s_cselect_b32 s55, s13, s53
	s_cselect_b32 s54, s91, s52
	v_add_u32_e32 v138, s58, v141
	s_cselect_b32 s53, s11, s94
	s_cselect_b32 s52, s92, s93
	s_add_i32 s81, 0, 0x14000
	ds_read_b128 v[144:147], v138
	ds_read_b128 v[148:151], v138 offset:1024
	ds_read_b128 v[152:155], v138 offset:2048
	ds_read_b128 v[156:159], v138 offset:3072
	v_add_u32_e32 v138, s81, v141
	ds_read_b128 v[160:163], v138
	ds_read_b128 v[164:167], v138 offset:1024
	ds_read_b128 v[168:171], v138 offset:2048
	ds_read_b128 v[174:177], v138 offset:3072
	v_lshl_add_u64 v[138:139], s[22:23], 0, v[134:135]
	s_add_i32 m0, s76, 0xc000
	ds_read_b128 v[178:181], v143
	ds_read_b128 v[182:185], v143 offset:1024
	ds_read_b128 v[186:189], v143 offset:2048
	ds_read_b128 v[190:193], v143 offset:3072
	ds_read_b128 v[194:197], v143 offset:4096
	ds_read_b128 v[198:201], v143 offset:5120
	ds_read_b128 v[202:205], v143 offset:6144
	ds_read_b128 v[206:209], v143 offset:7168
	global_load_lds_dwordx4 v[138:139], off
	v_lshl_add_u64 v[138:139], s[22:23], 0, v[136:137]
	s_add_i32 m0, s76, 0xe000
	s_nop 0
	global_load_lds_dwordx4 v[138:139], off
	s_waitcnt vmcnt(8)
	s_waitcnt lgkmcnt(0)
	s_barrier
	v_mfma_f32_16x16x32_bf16 v[120:123], v[144:147], v[178:181], 0
	v_mfma_f32_16x16x32_bf16 v[120:123], v[148:151], v[182:185], v[120:123]
	v_mfma_f32_16x16x32_bf16 v[104:107], v[144:147], v[186:189], 0
	v_mfma_f32_16x16x32_bf16 v[104:107], v[148:151], v[190:193], v[104:107]
	v_mfma_f32_16x16x32_bf16 v[88:91], v[144:147], v[194:197], 0
	v_mfma_f32_16x16x32_bf16 v[88:91], v[148:151], v[198:201], v[88:91]
	v_mfma_f32_16x16x32_bf16 v[72:75], v[144:147], v[202:205], 0
	v_mfma_f32_16x16x32_bf16 v[72:75], v[148:151], v[206:209], v[72:75]
	v_mfma_f32_16x16x32_bf16 v[112:115], v[152:155], v[178:181], 0
	v_mfma_f32_16x16x32_bf16 v[112:115], v[156:159], v[182:185], v[112:115]
	v_mfma_f32_16x16x32_bf16 v[96:99], v[152:155], v[186:189], 0
	v_mfma_f32_16x16x32_bf16 v[96:99], v[156:159], v[190:193], v[96:99]
	v_mfma_f32_16x16x32_bf16 v[80:83], v[152:155], v[194:197], 0
	v_mfma_f32_16x16x32_bf16 v[80:83], v[156:159], v[198:201], v[80:83]
	v_mfma_f32_16x16x32_bf16 v[64:67], v[152:155], v[202:205], 0
	v_mfma_f32_16x16x32_bf16 v[64:67], v[156:159], v[206:209], v[64:67]
	v_mfma_f32_16x16x32_bf16 v[124:127], v[160:163], v[178:181], 0
	v_mfma_f32_16x16x32_bf16 v[124:127], v[164:167], v[182:185], v[124:127]
	v_mfma_f32_16x16x32_bf16 v[108:111], v[160:163], v[186:189], 0
	v_mfma_f32_16x16x32_bf16 v[108:111], v[164:167], v[190:193], v[108:111]
	v_mfma_f32_16x16x32_bf16 v[92:95], v[160:163], v[194:197], 0
	v_mfma_f32_16x16x32_bf16 v[92:95], v[164:167], v[198:201], v[92:95]
	v_mfma_f32_16x16x32_bf16 v[76:79], v[160:163], v[202:205], 0
	v_mfma_f32_16x16x32_bf16 v[76:79], v[164:167], v[206:209], v[76:79]
	v_mfma_f32_16x16x32_bf16 v[116:119], v[168:171], v[178:181], 0
	v_mfma_f32_16x16x32_bf16 v[116:119], v[174:177], v[182:185], v[116:119]
	v_mfma_f32_16x16x32_bf16 v[100:103], v[168:171], v[186:189], 0
	v_mfma_f32_16x16x32_bf16 v[100:103], v[174:177], v[190:193], v[100:103]
	v_mfma_f32_16x16x32_bf16 v[84:87], v[168:171], v[194:197], 0
	v_mfma_f32_16x16x32_bf16 v[84:87], v[174:177], v[198:201], v[84:87]
	v_mfma_f32_16x16x32_bf16 v[68:71], v[168:171], v[202:205], 0
	v_mfma_f32_16x16x32_bf16 v[68:71], v[174:177], v[206:209], v[68:71]
	s_barrier
	s_add_i32 s58, s58, s50
	v_lshl_add_u64 v[138:139], s[52:53], 0, v[216:217]
	s_mov_b32 m0, s58
	ds_read_b128 v[178:181], v143 offset:16384
	ds_read_b128 v[182:185], v143 offset:17408
	ds_read_b128 v[186:189], v143 offset:18432
	ds_read_b128 v[190:193], v143 offset:19456
	ds_read_b128 v[194:197], v143 offset:20480
	ds_read_b128 v[198:201], v143 offset:21504
	ds_read_b128 v[202:205], v143 offset:22528
	ds_read_b128 v[206:209], v143 offset:23552
	global_load_lds_dwordx4 v[138:139], off
	s_add_i32 m0, s58, 0x2000
	s_add_u32 s58, s52, 0x80000
	v_lshl_add_u64 v[210:211], s[52:53], 0, v[132:133]
	s_addc_u32 s59, s53, 0
	s_add_i32 s81, s81, s50
	global_load_lds_dwordx4 v[210:211], off
	v_lshl_add_u64 v[212:213], s[58:59], 0, v[216:217]
	s_mov_b32 m0, s81
	v_lshl_add_u64 v[214:215], s[54:55], 0, v[130:131]
	global_load_lds_dwordx4 v[212:213], off
	v_lshl_add_u64 v[212:213], s[58:59], 0, v[132:133]
	s_add_i32 m0, s81, 0x2000
	s_nop 0
	global_load_lds_dwordx4 v[212:213], off
	v_lshl_add_u64 v[212:213], s[54:55], 0, v[128:129]
	s_mov_b32 m0, s76
	s_nop 0
	global_load_lds_dwordx4 v[212:213], off
	s_mov_b32 m0, s74
	s_nop 0
	global_load_lds_dwordx4 v[214:215], off
	s_waitcnt vmcnt(8)
	s_waitcnt lgkmcnt(0)
	s_barrier
	v_mfma_f32_16x16x32_bf16 v[56:59], v[144:147], v[178:181], 0
	v_mfma_f32_16x16x32_bf16 v[56:59], v[148:151], v[182:185], v[56:59]
	v_mfma_f32_16x16x32_bf16 v[40:43], v[144:147], v[186:189], 0
	v_mfma_f32_16x16x32_bf16 v[40:43], v[148:151], v[190:193], v[40:43]
	v_mfma_f32_16x16x32_bf16 v[24:27], v[144:147], v[194:197], 0
	v_mfma_f32_16x16x32_bf16 v[24:27], v[148:151], v[198:201], v[24:27]
	v_mfma_f32_16x16x32_bf16 v[8:11], v[144:147], v[202:205], 0
	v_mfma_f32_16x16x32_bf16 v[8:11], v[148:151], v[206:209], v[8:11]
	v_mfma_f32_16x16x32_bf16 v[48:51], v[152:155], v[178:181], 0
	v_mfma_f32_16x16x32_bf16 v[48:51], v[156:159], v[182:185], v[48:51]
	v_mfma_f32_16x16x32_bf16 v[32:35], v[152:155], v[186:189], 0
	v_mfma_f32_16x16x32_bf16 v[32:35], v[156:159], v[190:193], v[32:35]
	v_mfma_f32_16x16x32_bf16 v[16:19], v[152:155], v[194:197], 0
	v_mfma_f32_16x16x32_bf16 v[16:19], v[156:159], v[198:201], v[16:19]
	v_mfma_f32_16x16x32_bf16 v[0:3], v[152:155], v[202:205], 0
	v_mfma_f32_16x16x32_bf16 v[0:3], v[156:159], v[206:209], v[0:3]
	v_mfma_f32_16x16x32_bf16 v[60:63], v[160:163], v[178:181], 0
	v_mfma_f32_16x16x32_bf16 v[60:63], v[164:167], v[182:185], v[60:63]
	v_mfma_f32_16x16x32_bf16 v[44:47], v[160:163], v[186:189], 0
	v_mfma_f32_16x16x32_bf16 v[44:47], v[164:167], v[190:193], v[44:47]
	v_mfma_f32_16x16x32_bf16 v[28:31], v[160:163], v[194:197], 0
	v_mfma_f32_16x16x32_bf16 v[28:31], v[164:167], v[198:201], v[28:31]
	v_mfma_f32_16x16x32_bf16 v[12:15], v[160:163], v[202:205], 0
	v_mfma_f32_16x16x32_bf16 v[12:15], v[164:167], v[206:209], v[12:15]
	v_mfma_f32_16x16x32_bf16 v[52:55], v[168:171], v[178:181], 0
	v_mfma_f32_16x16x32_bf16 v[52:55], v[174:177], v[182:185], v[52:55]
	v_mfma_f32_16x16x32_bf16 v[36:39], v[168:171], v[186:189], 0
	v_mfma_f32_16x16x32_bf16 v[36:39], v[174:177], v[190:193], v[36:39]
	v_mfma_f32_16x16x32_bf16 v[20:23], v[168:171], v[194:197], 0
	v_mfma_f32_16x16x32_bf16 v[20:23], v[174:177], v[198:201], v[20:23]
	v_mfma_f32_16x16x32_bf16 v[4:7], v[168:171], v[202:205], 0
	v_mfma_f32_16x16x32_bf16 v[4:7], v[174:177], v[206:209], v[4:7]
	s_barrier
	s_add_i32 s58, 0, 0x18000
	s_add_i32 s59, 0, 0x1c000
	v_add_u32_e32 v156, s58, v141
	v_add_u32_e32 v173, s59, v141
	ds_read_b128 v[144:147], v156
	ds_read_b128 v[148:151], v156 offset:1024
	ds_read_b128 v[152:155], v156 offset:2048
	ds_read_b128 v[156:159], v156 offset:3072
	ds_read_b128 v[160:163], v173
	ds_read_b128 v[164:167], v173 offset:1024
	ds_read_b128 v[168:171], v173 offset:2048
	ds_read_b128 v[174:177], v173 offset:3072
	s_add_u32 s54, s54, 0x80000
	s_addc_u32 s55, s55, 0
	s_mov_b32 m0, s85
	v_lshl_add_u64 v[218:219], s[54:55], 0, v[128:129]
	ds_read_b128 v[178:181], v143 offset:32768
	ds_read_b128 v[182:185], v143 offset:33792
	ds_read_b128 v[186:189], v143 offset:34816
	ds_read_b128 v[190:193], v143 offset:35840
	ds_read_b128 v[194:197], v143 offset:36864
	ds_read_b128 v[198:201], v143 offset:37888
	ds_read_b128 v[202:205], v143 offset:38912
	ds_read_b128 v[206:209], v143 offset:39936
	global_load_lds_dwordx4 v[218:219], off
	v_lshl_add_u64 v[218:219], s[54:55], 0, v[130:131]
	s_mov_b32 m0, s86
	s_nop 0
	global_load_lds_dwordx4 v[218:219], off
	s_waitcnt vmcnt(8)
	s_waitcnt lgkmcnt(0)
	s_barrier
	v_mfma_f32_16x16x32_bf16 v[120:123], v[144:147], v[178:181], v[120:123]
	v_mfma_f32_16x16x32_bf16 v[120:123], v[148:151], v[182:185], v[120:123]
	v_mfma_f32_16x16x32_bf16 v[104:107], v[144:147], v[186:189], v[104:107]
	v_mfma_f32_16x16x32_bf16 v[104:107], v[148:151], v[190:193], v[104:107]
	v_mfma_f32_16x16x32_bf16 v[88:91], v[144:147], v[194:197], v[88:91]
	v_mfma_f32_16x16x32_bf16 v[88:91], v[148:151], v[198:201], v[88:91]
	v_mfma_f32_16x16x32_bf16 v[72:75], v[144:147], v[202:205], v[72:75]
	v_mfma_f32_16x16x32_bf16 v[72:75], v[148:151], v[206:209], v[72:75]
	v_mfma_f32_16x16x32_bf16 v[112:115], v[152:155], v[178:181], v[112:115]
	v_mfma_f32_16x16x32_bf16 v[112:115], v[156:159], v[182:185], v[112:115]
	v_mfma_f32_16x16x32_bf16 v[96:99], v[152:155], v[186:189], v[96:99]
	v_mfma_f32_16x16x32_bf16 v[96:99], v[156:159], v[190:193], v[96:99]
	v_mfma_f32_16x16x32_bf16 v[80:83], v[152:155], v[194:197], v[80:83]
	v_mfma_f32_16x16x32_bf16 v[80:83], v[156:159], v[198:201], v[80:83]
	v_mfma_f32_16x16x32_bf16 v[64:67], v[152:155], v[202:205], v[64:67]
	v_mfma_f32_16x16x32_bf16 v[64:67], v[156:159], v[206:209], v[64:67]
	v_mfma_f32_16x16x32_bf16 v[124:127], v[160:163], v[178:181], v[124:127]
	v_mfma_f32_16x16x32_bf16 v[124:127], v[164:167], v[182:185], v[124:127]
	v_mfma_f32_16x16x32_bf16 v[108:111], v[160:163], v[186:189], v[108:111]
	v_mfma_f32_16x16x32_bf16 v[108:111], v[164:167], v[190:193], v[108:111]
	v_mfma_f32_16x16x32_bf16 v[92:95], v[160:163], v[194:197], v[92:95]
	v_mfma_f32_16x16x32_bf16 v[92:95], v[164:167], v[198:201], v[92:95]
	v_mfma_f32_16x16x32_bf16 v[76:79], v[160:163], v[202:205], v[76:79]
	v_mfma_f32_16x16x32_bf16 v[76:79], v[164:167], v[206:209], v[76:79]
	v_mfma_f32_16x16x32_bf16 v[116:119], v[168:171], v[178:181], v[116:119]
	v_mfma_f32_16x16x32_bf16 v[116:119], v[174:177], v[182:185], v[116:119]
	v_mfma_f32_16x16x32_bf16 v[100:103], v[168:171], v[186:189], v[100:103]
	v_mfma_f32_16x16x32_bf16 v[100:103], v[174:177], v[190:193], v[100:103]
	v_mfma_f32_16x16x32_bf16 v[84:87], v[168:171], v[194:197], v[84:87]
	v_mfma_f32_16x16x32_bf16 v[84:87], v[174:177], v[198:201], v[84:87]
	v_mfma_f32_16x16x32_bf16 v[68:71], v[168:171], v[202:205], v[68:71]
	v_mfma_f32_16x16x32_bf16 v[68:71], v[174:177], v[206:209], v[68:71]
	s_barrier
	s_add_i32 s54, s58, s50
	v_lshl_add_u64 v[138:139], v[138:139], 0, s[60:61]
	s_mov_b32 m0, s54
	ds_read_b128 v[178:181], v143 offset:49152
	ds_read_b128 v[182:185], v143 offset:50176
	ds_read_b128 v[186:189], v143 offset:51200
	ds_read_b128 v[190:193], v143 offset:52224
	ds_read_b128 v[194:197], v143 offset:53248
	ds_read_b128 v[198:201], v143 offset:54272
	ds_read_b128 v[202:205], v143 offset:55296
	ds_read_b128 v[206:209], v143 offset:56320
	global_load_lds_dwordx4 v[138:139], off
	s_add_i32 m0, s54, 0x2000
	s_add_u32 s52, s52, 0x80080
	v_lshl_add_u64 v[138:139], v[210:211], 0, s[60:61]
	s_addc_u32 s53, s53, 0
	s_add_i32 s54, s59, s50
	global_load_lds_dwordx4 v[138:139], off
	v_lshl_add_u64 v[138:139], s[52:53], 0, v[216:217]
	s_mov_b32 m0, s54
	s_nop 0
	global_load_lds_dwordx4 v[138:139], off
	v_lshl_add_u64 v[138:139], s[52:53], 0, v[132:133]
	s_add_i32 m0, s54, 0x2000
	s_nop 0
	global_load_lds_dwordx4 v[138:139], off
	v_lshl_add_u64 v[138:139], v[212:213], 0, s[60:61]
	s_mov_b32 m0, s87
	s_nop 0
	global_load_lds_dwordx4 v[138:139], off
	v_lshl_add_u64 v[138:139], v[214:215], 0, s[60:61]
	s_mov_b32 m0, s88
	s_nop 0
	global_load_lds_dwordx4 v[138:139], off
	s_waitcnt vmcnt(8)
	s_waitcnt lgkmcnt(0)
	s_barrier
	v_mfma_f32_16x16x32_bf16 v[56:59], v[144:147], v[178:181], v[56:59]
	v_mfma_f32_16x16x32_bf16 v[56:59], v[148:151], v[182:185], v[56:59]
	v_mfma_f32_16x16x32_bf16 v[40:43], v[144:147], v[186:189], v[40:43]
	v_mfma_f32_16x16x32_bf16 v[40:43], v[148:151], v[190:193], v[40:43]
	v_mfma_f32_16x16x32_bf16 v[24:27], v[144:147], v[194:197], v[24:27]
	v_mfma_f32_16x16x32_bf16 v[24:27], v[148:151], v[198:201], v[24:27]
	v_mfma_f32_16x16x32_bf16 v[8:11], v[144:147], v[202:205], v[8:11]
	v_mfma_f32_16x16x32_bf16 v[8:11], v[148:151], v[206:209], v[8:11]
	v_mfma_f32_16x16x32_bf16 v[48:51], v[152:155], v[178:181], v[48:51]
	v_mfma_f32_16x16x32_bf16 v[48:51], v[156:159], v[182:185], v[48:51]
	v_mfma_f32_16x16x32_bf16 v[32:35], v[152:155], v[186:189], v[32:35]
	v_mfma_f32_16x16x32_bf16 v[32:35], v[156:159], v[190:193], v[32:35]
	v_mfma_f32_16x16x32_bf16 v[16:19], v[152:155], v[194:197], v[16:19]
	v_mfma_f32_16x16x32_bf16 v[16:19], v[156:159], v[198:201], v[16:19]
	v_mfma_f32_16x16x32_bf16 v[0:3], v[152:155], v[202:205], v[0:3]
	v_mfma_f32_16x16x32_bf16 v[0:3], v[156:159], v[206:209], v[0:3]
	v_mfma_f32_16x16x32_bf16 v[60:63], v[160:163], v[178:181], v[60:63]
	v_mfma_f32_16x16x32_bf16 v[60:63], v[164:167], v[182:185], v[60:63]
	v_mfma_f32_16x16x32_bf16 v[44:47], v[160:163], v[186:189], v[44:47]
	v_mfma_f32_16x16x32_bf16 v[44:47], v[164:167], v[190:193], v[44:47]
	v_mfma_f32_16x16x32_bf16 v[28:31], v[160:163], v[194:197], v[28:31]
	v_mfma_f32_16x16x32_bf16 v[28:31], v[164:167], v[198:201], v[28:31]
	v_mfma_f32_16x16x32_bf16 v[12:15], v[160:163], v[202:205], v[12:15]
	v_mfma_f32_16x16x32_bf16 v[12:15], v[164:167], v[206:209], v[12:15]
	v_mfma_f32_16x16x32_bf16 v[52:55], v[168:171], v[178:181], v[52:55]
	v_mfma_f32_16x16x32_bf16 v[52:55], v[174:177], v[182:185], v[52:55]
	v_mfma_f32_16x16x32_bf16 v[36:39], v[168:171], v[186:189], v[36:39]
	v_mfma_f32_16x16x32_bf16 v[36:39], v[174:177], v[190:193], v[36:39]
	v_mfma_f32_16x16x32_bf16 v[20:23], v[168:171], v[194:197], v[20:23]
	v_mfma_f32_16x16x32_bf16 v[20:23], v[174:177], v[198:201], v[20:23]
	v_mfma_f32_16x16x32_bf16 v[4:7], v[168:171], v[202:205], v[4:7]
	v_mfma_f32_16x16x32_bf16 v[4:7], v[174:177], v[206:209], v[4:7]
	s_barrier
	s_add_i32 s95, s95, 2
	s_add_u32 s22, s22, 0x100
	s_addc_u32 s23, s23, 0
	s_add_u32 s93, s93, 0x100
	s_addc_u32 s94, s94, 0
	s_cmp_gt_u32 s95, 29
	s_cbranch_scc0 .LBB0_1931
	s_branch .Lzexit_6

.LBB0_2080:
	s_add_u32 s93, s22, 0x100
	v_mov_b32_e32 v0, 0
	s_addc_u32 s94, s23, 0
	s_mov_b32 s95, -2
	s_add_u32 s22, s18, 0x100
	s_addc_u32 s23, s19, 0
	s_add_i32 s58, 0, 0x10000
	s_cmpk_eq_i32 s95, 0x54
	s_cselect_b32 s55, s7, s23
	s_cselect_b32 s54, s6, s22
	s_cselect_b32 s53, s17, s94
	s_cselect_b32 s52, s16, s93
	s_add_i32 s59, 0, 0x14000
	v_add_u32_e32 v140, s58, v195
	v_add_u32_e32 v166, s59, v195
	ds_read_b128 v[128:131], v140
	ds_read_b128 v[132:135], v140 offset:1024
	ds_read_b128 v[136:139], v140 offset:2048
	ds_read_b128 v[140:143], v140 offset:3072
	ds_read_b128 v[144:147], v166
	ds_read_b128 v[148:151], v166 offset:1024
	ds_read_b128 v[152:155], v166 offset:2048
	ds_read_b128 v[166:169], v166 offset:3072
	v_lshl_add_u64 v[206:207], s[18:19], 0, v[162:163]
	s_add_i32 m0, s76, 0xc000
	ds_read_b128 v[170:173], v197
	ds_read_b128 v[174:177], v197 offset:1024
	ds_read_b128 v[178:181], v197 offset:2048
	ds_read_b128 v[182:185], v197 offset:3072
	ds_read_b128 v[186:189], v197 offset:4096
	ds_read_b128 v[190:193], v197 offset:5120
	ds_read_b128 v[198:201], v197 offset:6144
	ds_read_b128 v[202:205], v197 offset:7168
	global_load_lds_dwordx4 v[206:207], off
	v_lshl_add_u64 v[206:207], s[18:19], 0, v[164:165]
	s_add_i32 m0, s76, 0xe000
	s_nop 0
	global_load_lds_dwordx4 v[206:207], off
	s_waitcnt vmcnt(8)
	s_waitcnt lgkmcnt(0)
	s_barrier
	v_mfma_f32_16x16x32_bf16 v[124:127], v[128:131], v[170:173], 0
	v_mfma_f32_16x16x32_bf16 v[124:127], v[132:135], v[174:177], v[124:127]
	v_mfma_f32_16x16x32_bf16 v[108:111], v[128:131], v[178:181], 0
	v_mfma_f32_16x16x32_bf16 v[108:111], v[132:135], v[182:185], v[108:111]
	v_mfma_f32_16x16x32_bf16 v[92:95], v[128:131], v[186:189], 0
	v_mfma_f32_16x16x32_bf16 v[92:95], v[132:135], v[190:193], v[92:95]
	v_mfma_f32_16x16x32_bf16 v[76:79], v[128:131], v[198:201], 0
	v_mfma_f32_16x16x32_bf16 v[76:79], v[132:135], v[202:205], v[76:79]
	v_mfma_f32_16x16x32_bf16 v[120:123], v[136:139], v[170:173], 0
	v_mfma_f32_16x16x32_bf16 v[120:123], v[140:143], v[174:177], v[120:123]
	v_mfma_f32_16x16x32_bf16 v[104:107], v[136:139], v[178:181], 0
	v_mfma_f32_16x16x32_bf16 v[104:107], v[140:143], v[182:185], v[104:107]
	v_mfma_f32_16x16x32_bf16 v[88:91], v[136:139], v[186:189], 0
	v_mfma_f32_16x16x32_bf16 v[88:91], v[140:143], v[190:193], v[88:91]
	v_mfma_f32_16x16x32_bf16 v[72:75], v[136:139], v[198:201], 0
	v_mfma_f32_16x16x32_bf16 v[72:75], v[140:143], v[202:205], v[72:75]
	v_mfma_f32_16x16x32_bf16 v[116:119], v[144:147], v[170:173], 0
	v_mfma_f32_16x16x32_bf16 v[116:119], v[148:151], v[174:177], v[116:119]
	v_mfma_f32_16x16x32_bf16 v[100:103], v[144:147], v[178:181], 0
	v_mfma_f32_16x16x32_bf16 v[100:103], v[148:151], v[182:185], v[100:103]
	v_mfma_f32_16x16x32_bf16 v[84:87], v[144:147], v[186:189], 0
	v_mfma_f32_16x16x32_bf16 v[84:87], v[148:151], v[190:193], v[84:87]
	v_mfma_f32_16x16x32_bf16 v[68:71], v[144:147], v[198:201], 0
	v_mfma_f32_16x16x32_bf16 v[68:71], v[148:151], v[202:205], v[68:71]
	v_mfma_f32_16x16x32_bf16 v[112:115], v[152:155], v[170:173], 0
	v_mfma_f32_16x16x32_bf16 v[112:115], v[166:169], v[174:177], v[112:115]
	v_mfma_f32_16x16x32_bf16 v[96:99], v[152:155], v[178:181], 0
	v_mfma_f32_16x16x32_bf16 v[96:99], v[166:169], v[182:185], v[96:99]
	v_mfma_f32_16x16x32_bf16 v[80:83], v[152:155], v[186:189], 0
	v_mfma_f32_16x16x32_bf16 v[80:83], v[166:169], v[190:193], v[80:83]
	v_mfma_f32_16x16x32_bf16 v[64:67], v[152:155], v[198:201], 0
	v_mfma_f32_16x16x32_bf16 v[64:67], v[166:169], v[202:205], v[64:67]
	s_barrier
	s_add_i32 s18, s58, s50
	v_lshl_add_u64 v[206:207], s[52:53], 0, v[216:217]
	s_mov_b32 m0, s18
	ds_read_b128 v[170:173], v197 offset:16384
	ds_read_b128 v[174:177], v197 offset:17408
	ds_read_b128 v[178:181], v197 offset:18432
	ds_read_b128 v[182:185], v197 offset:19456
	ds_read_b128 v[186:189], v197 offset:20480
	ds_read_b128 v[190:193], v197 offset:21504
	ds_read_b128 v[198:201], v197 offset:22528
	ds_read_b128 v[202:205], v197 offset:23552
	global_load_lds_dwordx4 v[206:207], off
	s_add_i32 m0, s18, 0x2000
	s_add_u32 s18, s52, 0x164000
	v_lshl_add_u64 v[208:209], s[52:53], 0, v[160:161]
	s_addc_u32 s19, s53, 0
	s_add_i32 s58, s59, s50
	global_load_lds_dwordx4 v[208:209], off
	v_lshl_add_u64 v[210:211], s[18:19], 0, v[216:217]
	s_mov_b32 m0, s58
	v_lshl_add_u64 v[212:213], s[54:55], 0, v[158:159]
	global_load_lds_dwordx4 v[210:211], off
	v_lshl_add_u64 v[210:211], s[18:19], 0, v[160:161]
	s_add_i32 m0, s58, 0x2000
	s_nop 0
	global_load_lds_dwordx4 v[210:211], off
	v_lshl_add_u64 v[210:211], s[54:55], 0, v[156:157]
	s_mov_b32 m0, s76
	s_nop 0
	global_load_lds_dwordx4 v[210:211], off
	s_mov_b32 m0, s45
	s_nop 0
	global_load_lds_dwordx4 v[212:213], off
	s_waitcnt vmcnt(8)
	s_waitcnt lgkmcnt(0)
	s_barrier
	v_mfma_f32_16x16x32_bf16 v[60:63], v[128:131], v[170:173], 0
	v_mfma_f32_16x16x32_bf16 v[60:63], v[132:135], v[174:177], v[60:63]
	v_mfma_f32_16x16x32_bf16 v[44:47], v[128:131], v[178:181], 0
	v_mfma_f32_16x16x32_bf16 v[44:47], v[132:135], v[182:185], v[44:47]
	v_mfma_f32_16x16x32_bf16 v[28:31], v[128:131], v[186:189], 0
	v_mfma_f32_16x16x32_bf16 v[28:31], v[132:135], v[190:193], v[28:31]
	v_mfma_f32_16x16x32_bf16 v[12:15], v[128:131], v[198:201], 0
	v_mfma_f32_16x16x32_bf16 v[12:15], v[132:135], v[202:205], v[12:15]
	v_mfma_f32_16x16x32_bf16 v[56:59], v[136:139], v[170:173], 0
	v_mfma_f32_16x16x32_bf16 v[56:59], v[140:143], v[174:177], v[56:59]
	v_mfma_f32_16x16x32_bf16 v[40:43], v[136:139], v[178:181], 0
	v_mfma_f32_16x16x32_bf16 v[40:43], v[140:143], v[182:185], v[40:43]
	v_mfma_f32_16x16x32_bf16 v[24:27], v[136:139], v[186:189], 0
	v_mfma_f32_16x16x32_bf16 v[24:27], v[140:143], v[190:193], v[24:27]
	v_mfma_f32_16x16x32_bf16 v[8:11], v[136:139], v[198:201], 0
	v_mfma_f32_16x16x32_bf16 v[8:11], v[140:143], v[202:205], v[8:11]
	v_mfma_f32_16x16x32_bf16 v[52:55], v[144:147], v[170:173], 0
	v_mfma_f32_16x16x32_bf16 v[52:55], v[148:151], v[174:177], v[52:55]
	v_mfma_f32_16x16x32_bf16 v[36:39], v[144:147], v[178:181], 0
	v_mfma_f32_16x16x32_bf16 v[36:39], v[148:151], v[182:185], v[36:39]
	v_mfma_f32_16x16x32_bf16 v[20:23], v[144:147], v[186:189], 0
	v_mfma_f32_16x16x32_bf16 v[20:23], v[148:151], v[190:193], v[20:23]
	v_mfma_f32_16x16x32_bf16 v[4:7], v[144:147], v[198:201], 0
	v_mfma_f32_16x16x32_bf16 v[4:7], v[148:151], v[202:205], v[4:7]
	v_mfma_f32_16x16x32_bf16 v[48:51], v[152:155], v[170:173], 0
	v_mfma_f32_16x16x32_bf16 v[48:51], v[166:169], v[174:177], v[48:51]
	v_mfma_f32_16x16x32_bf16 v[32:35], v[152:155], v[178:181], 0
	v_mfma_f32_16x16x32_bf16 v[32:35], v[166:169], v[182:185], v[32:35]
	v_mfma_f32_16x16x32_bf16 v[16:19], v[152:155], v[186:189], 0
	v_mfma_f32_16x16x32_bf16 v[16:19], v[166:169], v[190:193], v[16:19]
	v_mfma_f32_16x16x32_bf16 v[0:3], v[152:155], v[198:201], 0
	v_mfma_f32_16x16x32_bf16 v[0:3], v[166:169], v[202:205], v[0:3]
	s_barrier
	s_add_i32 s58, 0, 0x18000
	s_add_i32 s59, 0, 0x1c000
	v_add_u32_e32 v140, s58, v195
	v_add_u32_e32 v166, s59, v195
	ds_read_b128 v[128:131], v140
	ds_read_b128 v[132:135], v140 offset:1024
	ds_read_b128 v[136:139], v140 offset:2048
	ds_read_b128 v[140:143], v140 offset:3072
	ds_read_b128 v[144:147], v166
	ds_read_b128 v[148:151], v166 offset:1024
	ds_read_b128 v[152:155], v166 offset:2048
	ds_read_b128 v[166:169], v166 offset:3072
	s_add_u32 s18, s54, 0x164000
	s_addc_u32 s19, s55, 0
	s_mov_b32 m0, s64
	v_lshl_add_u64 v[214:215], s[18:19], 0, v[156:157]
	ds_read_b128 v[170:173], v197 offset:32768
	ds_read_b128 v[174:177], v197 offset:33792
	ds_read_b128 v[178:181], v197 offset:34816
	ds_read_b128 v[182:185], v197 offset:35840
	ds_read_b128 v[186:189], v197 offset:36864
	ds_read_b128 v[190:193], v197 offset:37888
	ds_read_b128 v[198:201], v197 offset:38912
	ds_read_b128 v[202:205], v197 offset:39936
	global_load_lds_dwordx4 v[214:215], off
	v_lshl_add_u64 v[214:215], s[18:19], 0, v[158:159]
	s_mov_b32 m0, s65
	s_nop 0
	global_load_lds_dwordx4 v[214:215], off
	s_waitcnt vmcnt(8)
	s_waitcnt lgkmcnt(0)
	s_barrier
	v_mfma_f32_16x16x32_bf16 v[124:127], v[128:131], v[170:173], v[124:127]
	v_mfma_f32_16x16x32_bf16 v[124:127], v[132:135], v[174:177], v[124:127]
	v_mfma_f32_16x16x32_bf16 v[108:111], v[128:131], v[178:181], v[108:111]
	v_mfma_f32_16x16x32_bf16 v[108:111], v[132:135], v[182:185], v[108:111]
	v_mfma_f32_16x16x32_bf16 v[92:95], v[128:131], v[186:189], v[92:95]
	v_mfma_f32_16x16x32_bf16 v[92:95], v[132:135], v[190:193], v[92:95]
	v_mfma_f32_16x16x32_bf16 v[76:79], v[128:131], v[198:201], v[76:79]
	v_mfma_f32_16x16x32_bf16 v[76:79], v[132:135], v[202:205], v[76:79]
	v_mfma_f32_16x16x32_bf16 v[120:123], v[136:139], v[170:173], v[120:123]
	v_mfma_f32_16x16x32_bf16 v[120:123], v[140:143], v[174:177], v[120:123]
	v_mfma_f32_16x16x32_bf16 v[104:107], v[136:139], v[178:181], v[104:107]
	v_mfma_f32_16x16x32_bf16 v[104:107], v[140:143], v[182:185], v[104:107]
	v_mfma_f32_16x16x32_bf16 v[88:91], v[136:139], v[186:189], v[88:91]
	v_mfma_f32_16x16x32_bf16 v[88:91], v[140:143], v[190:193], v[88:91]
	v_mfma_f32_16x16x32_bf16 v[72:75], v[136:139], v[198:201], v[72:75]
	v_mfma_f32_16x16x32_bf16 v[72:75], v[140:143], v[202:205], v[72:75]
	v_mfma_f32_16x16x32_bf16 v[116:119], v[144:147], v[170:173], v[116:119]
	v_mfma_f32_16x16x32_bf16 v[116:119], v[148:151], v[174:177], v[116:119]
	v_mfma_f32_16x16x32_bf16 v[100:103], v[144:147], v[178:181], v[100:103]
	v_mfma_f32_16x16x32_bf16 v[100:103], v[148:151], v[182:185], v[100:103]
	v_mfma_f32_16x16x32_bf16 v[84:87], v[144:147], v[186:189], v[84:87]
	v_mfma_f32_16x16x32_bf16 v[84:87], v[148:151], v[190:193], v[84:87]
	v_mfma_f32_16x16x32_bf16 v[68:71], v[144:147], v[198:201], v[68:71]
	v_mfma_f32_16x16x32_bf16 v[68:71], v[148:151], v[202:205], v[68:71]
	v_mfma_f32_16x16x32_bf16 v[112:115], v[152:155], v[170:173], v[112:115]
	v_mfma_f32_16x16x32_bf16 v[112:115], v[166:169], v[174:177], v[112:115]
	v_mfma_f32_16x16x32_bf16 v[96:99], v[152:155], v[178:181], v[96:99]
	v_mfma_f32_16x16x32_bf16 v[96:99], v[166:169], v[182:185], v[96:99]
	v_mfma_f32_16x16x32_bf16 v[80:83], v[152:155], v[186:189], v[80:83]
	v_mfma_f32_16x16x32_bf16 v[80:83], v[166:169], v[190:193], v[80:83]
	v_mfma_f32_16x16x32_bf16 v[64:67], v[152:155], v[198:201], v[64:67]
	v_mfma_f32_16x16x32_bf16 v[64:67], v[166:169], v[202:205], v[64:67]
	s_barrier
	s_add_i32 s18, s58, s50
	v_lshl_add_u64 v[206:207], v[206:207], 0, s[60:61]
	s_mov_b32 m0, s18
	ds_read_b128 v[170:173], v197 offset:49152
	ds_read_b128 v[174:177], v197 offset:50176
	ds_read_b128 v[178:181], v197 offset:51200
	ds_read_b128 v[182:185], v197 offset:52224
	ds_read_b128 v[186:189], v197 offset:53248
	ds_read_b128 v[190:193], v197 offset:54272
	ds_read_b128 v[198:201], v197 offset:55296
	ds_read_b128 v[202:205], v197 offset:56320
	global_load_lds_dwordx4 v[206:207], off
	s_add_i32 m0, s18, 0x2000
	s_add_u32 s18, s52, 0x164080
	v_lshl_add_u64 v[206:207], v[208:209], 0, s[60:61]
	s_addc_u32 s19, s53, 0
	s_add_i32 s52, s59, s50
	global_load_lds_dwordx4 v[206:207], off
	v_lshl_add_u64 v[206:207], s[18:19], 0, v[216:217]
	s_mov_b32 m0, s52
	s_nop 0
	global_load_lds_dwordx4 v[206:207], off
	v_lshl_add_u64 v[206:207], s[18:19], 0, v[160:161]
	s_add_i32 m0, s52, 0x2000
	s_nop 0
	global_load_lds_dwordx4 v[206:207], off
	v_lshl_add_u64 v[206:207], v[210:211], 0, s[60:61]
	s_mov_b32 m0, s85
	s_nop 0
	global_load_lds_dwordx4 v[206:207], off
	v_lshl_add_u64 v[206:207], v[212:213], 0, s[60:61]
	s_mov_b32 m0, s86
	s_nop 0
	global_load_lds_dwordx4 v[206:207], off
	s_waitcnt vmcnt(8)
	s_waitcnt lgkmcnt(0)
	s_barrier
	v_mfma_f32_16x16x32_bf16 v[60:63], v[128:131], v[170:173], v[60:63]
	v_mfma_f32_16x16x32_bf16 v[60:63], v[132:135], v[174:177], v[60:63]
	v_mfma_f32_16x16x32_bf16 v[44:47], v[128:131], v[178:181], v[44:47]
	v_mfma_f32_16x16x32_bf16 v[44:47], v[132:135], v[182:185], v[44:47]
	v_mfma_f32_16x16x32_bf16 v[28:31], v[128:131], v[186:189], v[28:31]
	v_mfma_f32_16x16x32_bf16 v[28:31], v[132:135], v[190:193], v[28:31]
	v_mfma_f32_16x16x32_bf16 v[12:15], v[128:131], v[198:201], v[12:15]
	v_mfma_f32_16x16x32_bf16 v[12:15], v[132:135], v[202:205], v[12:15]
	v_mfma_f32_16x16x32_bf16 v[56:59], v[136:139], v[170:173], v[56:59]
	v_mfma_f32_16x16x32_bf16 v[56:59], v[140:143], v[174:177], v[56:59]
	v_mfma_f32_16x16x32_bf16 v[40:43], v[136:139], v[178:181], v[40:43]
	v_mfma_f32_16x16x32_bf16 v[40:43], v[140:143], v[182:185], v[40:43]
	v_mfma_f32_16x16x32_bf16 v[24:27], v[136:139], v[186:189], v[24:27]
	v_mfma_f32_16x16x32_bf16 v[24:27], v[140:143], v[190:193], v[24:27]
	v_mfma_f32_16x16x32_bf16 v[8:11], v[136:139], v[198:201], v[8:11]
	v_mfma_f32_16x16x32_bf16 v[8:11], v[140:143], v[202:205], v[8:11]
	v_mfma_f32_16x16x32_bf16 v[52:55], v[144:147], v[170:173], v[52:55]
	v_mfma_f32_16x16x32_bf16 v[52:55], v[148:151], v[174:177], v[52:55]
	v_mfma_f32_16x16x32_bf16 v[36:39], v[144:147], v[178:181], v[36:39]
	v_mfma_f32_16x16x32_bf16 v[36:39], v[148:151], v[182:185], v[36:39]
	v_mfma_f32_16x16x32_bf16 v[20:23], v[144:147], v[186:189], v[20:23]
	v_mfma_f32_16x16x32_bf16 v[20:23], v[148:151], v[190:193], v[20:23]
	v_mfma_f32_16x16x32_bf16 v[4:7], v[144:147], v[198:201], v[4:7]
	v_mfma_f32_16x16x32_bf16 v[4:7], v[148:151], v[202:205], v[4:7]
	v_mfma_f32_16x16x32_bf16 v[48:51], v[152:155], v[170:173], v[48:51]
	v_mfma_f32_16x16x32_bf16 v[48:51], v[166:169], v[174:177], v[48:51]
	v_mfma_f32_16x16x32_bf16 v[32:35], v[152:155], v[178:181], v[32:35]
	v_mfma_f32_16x16x32_bf16 v[32:35], v[166:169], v[182:185], v[32:35]
	v_mfma_f32_16x16x32_bf16 v[16:19], v[152:155], v[186:189], v[16:19]
	v_mfma_f32_16x16x32_bf16 v[16:19], v[166:169], v[190:193], v[16:19]
	v_mfma_f32_16x16x32_bf16 v[0:3], v[152:155], v[198:201], v[0:3]
	v_mfma_f32_16x16x32_bf16 v[0:3], v[166:169], v[202:205], v[0:3]
	s_barrier
	s_add_i32 s95, s95, 2
	s_add_u32 s93, s93, 0x100
	s_addc_u32 s94, s94, 0
	s_cmpk_gt_u32 s95, 0x55
	s_mov_b64 s[18:19], s[22:23]
	s_cbranch_scc0 .LBB0_2081
	s_branch .Lzexit_7
